# GEMM mainloops: MFMAs reordered so the two K-halves of each accumulator issue back to back (SrcC forwarding chain)
# speedup vs baseline: 1.0083x; 1.0048x over previous
; #define PG8_STAGE(bufoff, gbase, voff) do { _Pragma("unroll") for (int _i = 0; _i < 2; ++_i) \
;         __builtin_amdgcn_global_load_lds((const unsigned*)((const char*)(gbase) + (voff)[_i]), (PG8_LAS unsigned*)(lds + (bufoff) + ldsw + _i * 8192), 16, 0, 0); } while (0)
; #define PG8_LDA(dst, b, h) do { _Pragma("unroll") for (int m = 0; m < 4; ++m) _Pragma("unroll") for (int k = 0; k < 2; ++k) dst[m][k] = *(const PG8_LAS bf16x8*)(lds + PG8_SA(b, h) + aoff + m * 2048 + k * 1024); } while (0)
; #define PG8_LDB(dst, b, h) do { _Pragma("unroll") for (int n = 0; n < 2; ++n) _Pragma("unroll") for (int k = 0; k < 2; ++k) dst[n][k] = *(const PG8_LAS bf16x8*)(lds + PG8_SB(b, h) + boff + n * 2048 + k * 1024); } while (0)
; #define PG8_MMA(ai, bj, At, Bt) do { __builtin_amdgcn_s_setprio(1); _Pragma("unroll") for (int m = 0; m < 4; ++m) _Pragma("unroll") for (int n = 0; n < 2; ++n) _Pragma("unroll") for (int k = 0; k < 2; ++k) \
;         acc[ai][bj][m][n] = __builtin_amdgcn_mfma_f32_16x16x32_bf16(Bt[n][k], At[m][k], acc[ai][bj][m][n], 0, 0, 0); __builtin_amdgcn_s_setprio(0); } while (0)
; #define PG8_WAIT_V(n) asm volatile("s_waitcnt vmcnt(" #n ")" ::: "memory")
; template <class Epi, class Sched, bool ALIGN_EPI = false, bool SP2 = false>
; __device__ __forceinline__ void gemm_phase(PG8_LAS unsigned char* lds, const Gemm g, const Sched& S, const Epi& E) {
;     ...
;             PG8_LDB(B0, 0, 0); PG8_LDB(B1, 0, 1); PG8_SCHED; PG8_LDA(At, 0, 0); PG8_STAGE(PG8_SA(1, 1), a1 + hstepA, voffA);
;             PG8_WAIT_V(8); PG8_WAIT_L(0); PG8_BAR; PG8_MMA(0, 0, At, B0); PG8_MMA(0, 1, At, B1); PG8_BAR; PG8_SCHED;
;             PG8_LDA(At, 0, 1); PG8_STAGE(PG8_SB(0, 0), b2, voffB); PG8_STAGE(PG8_SB(0, 1), b2 + hstepB, voffB); PG8_STAGE(PG8_SA(0, 0), a2, voffA);
;             PG8_WAIT_V(8); PG8_WAIT_L(0); PG8_BAR; PG8_MMA(1, 0, At, B0); PG8_MMA(1, 1, At, B1); PG8_BAR; PG8_SCHED;
;             PG8_LDB(B0, 1, 0); PG8_LDB(B1, 1, 1); PG8_SCHED; PG8_LDA(At, 1, 0); PG8_STAGE(PG8_SA(0, 1), a2 + hstepA, voffA);
;             PG8_WAIT_V(8); PG8_WAIT_L(0); PG8_BAR; PG8_MMA(0, 0, At, B0); PG8_MMA(0, 1, At, B1); PG8_BAR; PG8_SCHED;
;             PG8_LDA(At, 1, 1); PG8_STAGE(PG8_SB(1, 0), b3, voffB); PG8_STAGE(PG8_SB(1, 1), b3 + hstepB, voffB); PG8_STAGE(PG8_SA(1, 0), a3, voffA);
;             PG8_WAIT_V(8); PG8_WAIT_L(0); PG8_BAR; PG8_MMA(1, 0, At, B0); PG8_MMA(1, 1, At, B1); PG8_BAR; PG8_SCHED;
.LBB0_297:
	s_add_u32 s2, s8, 0xffe00080
	s_addc_u32 s10, s9, -1
	s_add_i32 s33, s17, 0x100
	s_cmpk_eq_i32 vcc_lo, 0x7c
	s_cselect_b32 s61, s49, s10
	s_cselect_b32 s60, s70, s2
	v_add_u32_e32 v144, s33, v147
	s_cselect_b32 s11, s47, s93
	s_cselect_b32 s10, s74, s91
	s_add_i32 s2, s24, 0x100
	ds_read_b128 v[136:139], v144
	ds_read_b128 v[140:143], v144 offset:1024
	ds_read_b128 v[150:153], v144 offset:2048
	ds_read_b128 v[154:157], v144 offset:3072
	v_add_u32_e32 v144, s2, v147
	ds_read_b128 v[158:161], v144
	ds_read_b128 v[162:165], v144 offset:1024
	ds_read_b128 v[166:169], v144 offset:2048
	ds_read_b128 v[170:173], v144 offset:3072
	v_lshl_add_u64 v[144:145], s[8:9], 0, v[132:133]
	s_add_i32 m0, s63, 0xc000
	ds_read_b128 v[174:177], v149
	ds_read_b128 v[178:181], v149 offset:1024
	ds_read_b128 v[182:185], v149 offset:2048
	ds_read_b128 v[186:189], v149 offset:3072
	ds_read_b128 v[190:193], v149 offset:4096
	ds_read_b128 v[210:213], v149 offset:5120
	ds_read_b128 v[222:225], v149 offset:6144
	ds_read_b128 v[228:231], v149 offset:7168
	global_load_lds_dwordx4 v[144:145], off
	v_lshl_add_u64 v[144:145], s[8:9], 0, v[134:135]
	s_add_i32 m0, s63, 0xe000
	s_nop 0
	global_load_lds_dwordx4 v[144:145], off
	s_waitcnt vmcnt(8)
	s_waitcnt lgkmcnt(0)
	s_barrier
	s_setprio 1
	s_waitcnt lgkmcnt(0)
	v_mfma_f32_16x16x32_bf16 v[126:129], v[136:139], v[174:177], v[126:129]
	v_mfma_f32_16x16x32_bf16 v[126:129], v[140:143], v[178:181], v[126:129]
	v_mfma_f32_16x16x32_bf16 v[122:125], v[150:153], v[174:177], v[122:125]
	v_mfma_f32_16x16x32_bf16 v[122:125], v[154:157], v[178:181], v[122:125]
	v_mfma_f32_16x16x32_bf16 v[110:113], v[136:139], v[182:185], v[110:113]
	v_mfma_f32_16x16x32_bf16 v[110:113], v[140:143], v[186:189], v[110:113]
	v_mfma_f32_16x16x32_bf16 v[106:109], v[150:153], v[182:185], v[106:109]
	v_mfma_f32_16x16x32_bf16 v[106:109], v[154:157], v[186:189], v[106:109]
	v_mfma_f32_16x16x32_bf16 v[94:97], v[136:139], v[190:193], v[94:97]
	v_mfma_f32_16x16x32_bf16 v[94:97], v[140:143], v[210:213], v[94:97]
	v_mfma_f32_16x16x32_bf16 v[90:93], v[150:153], v[190:193], v[90:93]
	v_mfma_f32_16x16x32_bf16 v[90:93], v[154:157], v[210:213], v[90:93]
	v_mfma_f32_16x16x32_bf16 v[78:81], v[136:139], v[222:225], v[78:81]
	v_mfma_f32_16x16x32_bf16 v[78:81], v[140:143], v[228:231], v[78:81]
	v_mfma_f32_16x16x32_bf16 v[74:77], v[150:153], v[222:225], v[74:77]
	v_mfma_f32_16x16x32_bf16 v[74:77], v[154:157], v[228:231], v[74:77]
	s_setprio 0
	s_setprio 1
	v_mfma_f32_16x16x32_bf16 v[118:121], v[158:161], v[174:177], v[118:121]
	v_mfma_f32_16x16x32_bf16 v[118:121], v[162:165], v[178:181], v[118:121]
	v_mfma_f32_16x16x32_bf16 v[114:117], v[166:169], v[174:177], v[114:117]
	v_mfma_f32_16x16x32_bf16 v[114:117], v[170:173], v[178:181], v[114:117]
	v_mfma_f32_16x16x32_bf16 v[102:105], v[158:161], v[182:185], v[102:105]
	v_mfma_f32_16x16x32_bf16 v[102:105], v[162:165], v[186:189], v[102:105]
	v_mfma_f32_16x16x32_bf16 v[98:101], v[166:169], v[182:185], v[98:101]
	v_mfma_f32_16x16x32_bf16 v[98:101], v[170:173], v[186:189], v[98:101]
	v_mfma_f32_16x16x32_bf16 v[86:89], v[158:161], v[190:193], v[86:89]
	v_mfma_f32_16x16x32_bf16 v[86:89], v[162:165], v[210:213], v[86:89]
	v_mfma_f32_16x16x32_bf16 v[82:85], v[166:169], v[190:193], v[82:85]
	v_mfma_f32_16x16x32_bf16 v[82:85], v[170:173], v[210:213], v[82:85]
	v_mfma_f32_16x16x32_bf16 v[70:73], v[158:161], v[222:225], v[70:73]
	v_mfma_f32_16x16x32_bf16 v[70:73], v[162:165], v[228:231], v[70:73]
	v_mfma_f32_16x16x32_bf16 v[66:69], v[166:169], v[222:225], v[66:69]
	v_mfma_f32_16x16x32_bf16 v[66:69], v[170:173], v[228:231], v[66:69]
	s_setprio 0
	s_barrier
	s_add_i32 s33, s33, s36
	v_lshl_add_u64 v[144:145], s[10:11], 0, v[0:1]
	s_mov_b32 m0, s33
	ds_read_b128 v[174:177], v149 offset:16384
	ds_read_b128 v[178:181], v149 offset:17408
	ds_read_b128 v[182:185], v149 offset:18432
	ds_read_b128 v[186:189], v149 offset:19456
	ds_read_b128 v[190:193], v149 offset:20480
	ds_read_b128 v[210:213], v149 offset:21504
	ds_read_b128 v[222:225], v149 offset:22528
	ds_read_b128 v[228:231], v149 offset:23552
	global_load_lds_dwordx4 v[144:145], off
	s_add_i32 m0, s33, 0x2000
	s_add_u32 s78, s10, 0x200000
	v_lshl_add_u64 v[194:195], s[10:11], 0, v[130:131]
	s_addc_u32 s79, s11, 0
	s_add_i32 s2, s2, s36
	global_load_lds_dwordx4 v[194:195], off
	v_lshl_add_u64 v[214:215], s[78:79], 0, v[0:1]
	s_mov_b32 m0, s2
	v_lshl_add_u64 v[232:233], s[60:61], 0, v[130:131]
	global_load_lds_dwordx4 v[214:215], off
	v_lshl_add_u64 v[214:215], s[78:79], 0, v[130:131]
	s_add_i32 m0, s2, 0x2000
	s_nop 0
	global_load_lds_dwordx4 v[214:215], off
	v_lshl_add_u64 v[214:215], s[60:61], 0, v[0:1]
	s_mov_b32 m0, s63
	s_nop 0
	global_load_lds_dwordx4 v[214:215], off
	s_mov_b32 m0, s65
	s_nop 0
	global_load_lds_dwordx4 v[232:233], off
	s_waitcnt vmcnt(8)
	s_waitcnt lgkmcnt(0)
	s_barrier
; #define PG8_STAGE(bufoff, gbase, voff) do { _Pragma("unroll") for (int _i = 0; _i < 2; ++_i) \
;         __builtin_amdgcn_global_load_lds((const unsigned*)((const char*)(gbase) + (voff)[_i]), (PG8_LAS unsigned*)(lds + (bufoff) + ldsw + _i * 8192), 16, 0, 0); } while (0)
; #define PG8_LDA(dst, b, h) do { _Pragma("unroll") for (int m = 0; m < 4; ++m) _Pragma("unroll") for (int k = 0; k < 2; ++k) dst[m][k] = *(const PG8_LAS bf16x8*)(lds + PG8_SA(b, h) + aoff + m * 2048 + k * 1024); } while (0)
; #define PG8_LDB(dst, b, h) do { _Pragma("unroll") for (int n = 0; n < 2; ++n) _Pragma("unroll") for (int k = 0; k < 2; ++k) dst[n][k] = *(const PG8_LAS bf16x8*)(lds + PG8_SB(b, h) + boff + n * 2048 + k * 1024); } while (0)
; #define PG8_MMA(ai, bj, At, Bt) do { __builtin_amdgcn_s_setprio(1); _Pragma("unroll") for (int m = 0; m < 4; ++m) _Pragma("unroll") for (int n = 0; n < 2; ++n) _Pragma("unroll") for (int k = 0; k < 2; ++k) \
;         acc[ai][bj][m][n] = __builtin_amdgcn_mfma_f32_16x16x32_bf16(Bt[n][k], At[m][k], acc[ai][bj][m][n], 0, 0, 0); __builtin_amdgcn_s_setprio(0); } while (0)
; #define PG8_WAIT_V(n) asm volatile("s_waitcnt vmcnt(" #n ")" ::: "memory")
; template <class Epi, class Sched, bool ALIGN_EPI = false, bool SP2 = false>
; __device__ __forceinline__ void gemm_phase(PG8_LAS unsigned char* lds, const Gemm g, const Sched& S, const Epi& E) {
;     ...
;             PG8_LDB(B0, 0, 0); PG8_LDB(B1, 0, 1); PG8_SCHED; PG8_LDA(At, 0, 0); PG8_STAGE(PG8_SA(1, 1), a1 + hstepA, voffA);
;             PG8_WAIT_V(8); PG8_WAIT_L(0); PG8_BAR; PG8_MMA(0, 0, At, B0); PG8_MMA(0, 1, At, B1); PG8_BAR; PG8_SCHED;
;             PG8_LDA(At, 0, 1); PG8_STAGE(PG8_SB(0, 0), b2, voffB); PG8_STAGE(PG8_SB(0, 1), b2 + hstepB, voffB); PG8_STAGE(PG8_SA(0, 0), a2, voffA);
;             PG8_WAIT_V(8); PG8_WAIT_L(0); PG8_BAR; PG8_MMA(1, 0, At, B0); PG8_MMA(1, 1, At, B1); PG8_BAR; PG8_SCHED;
;             PG8_LDB(B0, 1, 0); PG8_LDB(B1, 1, 1); PG8_SCHED; PG8_LDA(At, 1, 0); PG8_STAGE(PG8_SA(0, 1), a2 + hstepA, voffA);
;             PG8_WAIT_V(8); PG8_WAIT_L(0); PG8_BAR; PG8_MMA(0, 0, At, B0); PG8_MMA(0, 1, At, B1); PG8_BAR; PG8_SCHED;
;             PG8_LDA(At, 1, 1); PG8_STAGE(PG8_SB(1, 0), b3, voffB); PG8_STAGE(PG8_SB(1, 1), b3 + hstepB, voffB); PG8_STAGE(PG8_SA(1, 0), a3, voffA);
;             PG8_WAIT_V(8); PG8_WAIT_L(0); PG8_BAR; PG8_MMA(1, 0, At, B0); PG8_MMA(1, 1, At, B1); PG8_BAR; PG8_SCHED;
	s_setprio 1
	s_waitcnt lgkmcnt(0)
	v_mfma_f32_16x16x32_bf16 v[62:65], v[136:139], v[174:177], v[62:65]
	v_mfma_f32_16x16x32_bf16 v[62:65], v[140:143], v[178:181], v[62:65]
	v_mfma_f32_16x16x32_bf16 v[58:61], v[150:153], v[174:177], v[58:61]
	v_mfma_f32_16x16x32_bf16 v[58:61], v[154:157], v[178:181], v[58:61]
	v_mfma_f32_16x16x32_bf16 v[46:49], v[136:139], v[182:185], v[46:49]
	v_mfma_f32_16x16x32_bf16 v[46:49], v[140:143], v[186:189], v[46:49]
	v_mfma_f32_16x16x32_bf16 v[42:45], v[150:153], v[182:185], v[42:45]
	v_mfma_f32_16x16x32_bf16 v[42:45], v[154:157], v[186:189], v[42:45]
	v_mfma_f32_16x16x32_bf16 v[30:33], v[136:139], v[190:193], v[30:33]
	v_mfma_f32_16x16x32_bf16 v[30:33], v[140:143], v[210:213], v[30:33]
	v_mfma_f32_16x16x32_bf16 v[26:29], v[150:153], v[190:193], v[26:29]
	v_mfma_f32_16x16x32_bf16 v[26:29], v[154:157], v[210:213], v[26:29]
	v_mfma_f32_16x16x32_bf16 v[14:17], v[136:139], v[222:225], v[14:17]
	v_mfma_f32_16x16x32_bf16 v[14:17], v[140:143], v[228:231], v[14:17]
	v_mfma_f32_16x16x32_bf16 v[10:13], v[150:153], v[222:225], v[10:13]
	v_mfma_f32_16x16x32_bf16 v[10:13], v[154:157], v[228:231], v[10:13]
	s_setprio 0
	s_setprio 1
	v_mfma_f32_16x16x32_bf16 v[54:57], v[158:161], v[174:177], v[54:57]
	v_mfma_f32_16x16x32_bf16 v[54:57], v[162:165], v[178:181], v[54:57]
	v_mfma_f32_16x16x32_bf16 v[50:53], v[166:169], v[174:177], v[50:53]
	v_mfma_f32_16x16x32_bf16 v[50:53], v[170:173], v[178:181], v[50:53]
	v_mfma_f32_16x16x32_bf16 v[38:41], v[158:161], v[182:185], v[38:41]
	v_mfma_f32_16x16x32_bf16 v[38:41], v[162:165], v[186:189], v[38:41]
	v_mfma_f32_16x16x32_bf16 v[34:37], v[166:169], v[182:185], v[34:37]
	v_mfma_f32_16x16x32_bf16 v[34:37], v[170:173], v[186:189], v[34:37]
	v_mfma_f32_16x16x32_bf16 v[22:25], v[158:161], v[190:193], v[22:25]
	v_mfma_f32_16x16x32_bf16 v[22:25], v[162:165], v[210:213], v[22:25]
	v_mfma_f32_16x16x32_bf16 v[18:21], v[166:169], v[190:193], v[18:21]
	v_mfma_f32_16x16x32_bf16 v[18:21], v[170:173], v[210:213], v[18:21]
	v_mfma_f32_16x16x32_bf16 v[6:9], v[158:161], v[222:225], v[6:9]
	v_mfma_f32_16x16x32_bf16 v[6:9], v[162:165], v[228:231], v[6:9]
	v_mfma_f32_16x16x32_bf16 v[2:5], v[166:169], v[222:225], v[2:5]
	v_mfma_f32_16x16x32_bf16 v[2:5], v[170:173], v[228:231], v[2:5]
	s_setprio 0
	s_barrier
	s_add_i32 s2, s87, 0x100
	s_add_i32 s33, s69, 0x100
	v_add_u32_e32 v154, s2, v147
	v_add_u32_e32 v170, s33, v147
	ds_read_b128 v[136:139], v154
	ds_read_b128 v[140:143], v154 offset:1024
	ds_read_b128 v[150:153], v154 offset:2048
	ds_read_b128 v[154:157], v154 offset:3072
	ds_read_b128 v[158:161], v170
	ds_read_b128 v[162:165], v170 offset:1024
	ds_read_b128 v[166:169], v170 offset:2048
	ds_read_b128 v[170:173], v170 offset:3072
	s_add_u32 s60, s60, 0x200000
	s_addc_u32 s61, s61, 0
	s_mov_b32 m0, s72
	v_lshl_add_u64 v[234:235], s[60:61], 0, v[0:1]
	ds_read_b128 v[174:177], v149 offset:32768
	ds_read_b128 v[178:181], v149 offset:33792
	ds_read_b128 v[182:185], v149 offset:34816
	ds_read_b128 v[186:189], v149 offset:35840
	ds_read_b128 v[190:193], v149 offset:36864
	ds_read_b128 v[210:213], v149 offset:37888
	ds_read_b128 v[222:225], v149 offset:38912
	ds_read_b128 v[228:231], v149 offset:39936
	global_load_lds_dwordx4 v[234:235], off
	v_lshl_add_u64 v[234:235], s[60:61], 0, v[130:131]
	s_mov_b32 m0, s73
	s_nop 0
	global_load_lds_dwordx4 v[234:235], off
	s_waitcnt vmcnt(8)
	s_waitcnt lgkmcnt(0)
	s_barrier
	s_setprio 1
	s_waitcnt lgkmcnt(0)
	v_mfma_f32_16x16x32_bf16 v[126:129], v[136:139], v[174:177], v[126:129]
	v_mfma_f32_16x16x32_bf16 v[126:129], v[140:143], v[178:181], v[126:129]
	v_mfma_f32_16x16x32_bf16 v[122:125], v[150:153], v[174:177], v[122:125]
	v_mfma_f32_16x16x32_bf16 v[122:125], v[154:157], v[178:181], v[122:125]
	v_mfma_f32_16x16x32_bf16 v[110:113], v[136:139], v[182:185], v[110:113]
	v_mfma_f32_16x16x32_bf16 v[110:113], v[140:143], v[186:189], v[110:113]
	v_mfma_f32_16x16x32_bf16 v[106:109], v[150:153], v[182:185], v[106:109]
	v_mfma_f32_16x16x32_bf16 v[106:109], v[154:157], v[186:189], v[106:109]
	v_mfma_f32_16x16x32_bf16 v[94:97], v[136:139], v[190:193], v[94:97]
	v_mfma_f32_16x16x32_bf16 v[94:97], v[140:143], v[210:213], v[94:97]
	v_mfma_f32_16x16x32_bf16 v[90:93], v[150:153], v[190:193], v[90:93]
	v_mfma_f32_16x16x32_bf16 v[90:93], v[154:157], v[210:213], v[90:93]
	v_mfma_f32_16x16x32_bf16 v[78:81], v[136:139], v[222:225], v[78:81]
	v_mfma_f32_16x16x32_bf16 v[78:81], v[140:143], v[228:231], v[78:81]
	v_mfma_f32_16x16x32_bf16 v[74:77], v[150:153], v[222:225], v[74:77]
	v_mfma_f32_16x16x32_bf16 v[74:77], v[154:157], v[228:231], v[74:77]
	s_setprio 0
	s_setprio 1
	v_mfma_f32_16x16x32_bf16 v[118:121], v[158:161], v[174:177], v[118:121]
	v_mfma_f32_16x16x32_bf16 v[118:121], v[162:165], v[178:181], v[118:121]
	v_mfma_f32_16x16x32_bf16 v[114:117], v[166:169], v[174:177], v[114:117]
	v_mfma_f32_16x16x32_bf16 v[114:117], v[170:173], v[178:181], v[114:117]
	v_mfma_f32_16x16x32_bf16 v[102:105], v[158:161], v[182:185], v[102:105]
	v_mfma_f32_16x16x32_bf16 v[102:105], v[162:165], v[186:189], v[102:105]
	v_mfma_f32_16x16x32_bf16 v[98:101], v[166:169], v[182:185], v[98:101]
	v_mfma_f32_16x16x32_bf16 v[98:101], v[170:173], v[186:189], v[98:101]
	v_mfma_f32_16x16x32_bf16 v[86:89], v[158:161], v[190:193], v[86:89]
	v_mfma_f32_16x16x32_bf16 v[86:89], v[162:165], v[210:213], v[86:89]
	v_mfma_f32_16x16x32_bf16 v[82:85], v[166:169], v[190:193], v[82:85]
	v_mfma_f32_16x16x32_bf16 v[82:85], v[170:173], v[210:213], v[82:85]
	v_mfma_f32_16x16x32_bf16 v[70:73], v[158:161], v[222:225], v[70:73]
	v_mfma_f32_16x16x32_bf16 v[70:73], v[162:165], v[228:231], v[70:73]
	v_mfma_f32_16x16x32_bf16 v[66:69], v[166:169], v[222:225], v[66:69]
	v_mfma_f32_16x16x32_bf16 v[66:69], v[170:173], v[228:231], v[66:69]
	s_setprio 0
	s_barrier
; #define PG8_STAGE(bufoff, gbase, voff) do { _Pragma("unroll") for (int _i = 0; _i < 2; ++_i) \
;         __builtin_amdgcn_global_load_lds((const unsigned*)((const char*)(gbase) + (voff)[_i]), (PG8_LAS unsigned*)(lds + (bufoff) + ldsw + _i * 8192), 16, 0, 0); } while (0)
; #define PG8_LDA(dst, b, h) do { _Pragma("unroll") for (int m = 0; m < 4; ++m) _Pragma("unroll") for (int k = 0; k < 2; ++k) dst[m][k] = *(const PG8_LAS bf16x8*)(lds + PG8_SA(b, h) + aoff + m * 2048 + k * 1024); } while (0)
; #define PG8_LDB(dst, b, h) do { _Pragma("unroll") for (int n = 0; n < 2; ++n) _Pragma("unroll") for (int k = 0; k < 2; ++k) dst[n][k] = *(const PG8_LAS bf16x8*)(lds + PG8_SB(b, h) + boff + n * 2048 + k * 1024); } while (0)
; #define PG8_MMA(ai, bj, At, Bt) do { __builtin_amdgcn_s_setprio(1); _Pragma("unroll") for (int m = 0; m < 4; ++m) _Pragma("unroll") for (int n = 0; n < 2; ++n) _Pragma("unroll") for (int k = 0; k < 2; ++k) \
;         acc[ai][bj][m][n] = __builtin_amdgcn_mfma_f32_16x16x32_bf16(Bt[n][k], At[m][k], acc[ai][bj][m][n], 0, 0, 0); __builtin_amdgcn_s_setprio(0); } while (0)
; #define PG8_WAIT_V(n) asm volatile("s_waitcnt vmcnt(" #n ")" ::: "memory")
; template <class Epi, class Sched, bool ALIGN_EPI = false, bool SP2 = false>
; __device__ __forceinline__ void gemm_phase(PG8_LAS unsigned char* lds, const Gemm g, const Sched& S, const Epi& E) {
;     ...
;             PG8_LDB(B0, 0, 0); PG8_LDB(B1, 0, 1); PG8_SCHED; PG8_LDA(At, 0, 0); PG8_STAGE(PG8_SA(1, 1), a1 + hstepA, voffA);
;             PG8_WAIT_V(8); PG8_WAIT_L(0); PG8_BAR; PG8_MMA(0, 0, At, B0); PG8_MMA(0, 1, At, B1); PG8_BAR; PG8_SCHED;
;             PG8_LDA(At, 0, 1); PG8_STAGE(PG8_SB(0, 0), b2, voffB); PG8_STAGE(PG8_SB(0, 1), b2 + hstepB, voffB); PG8_STAGE(PG8_SA(0, 0), a2, voffA);
;             PG8_WAIT_V(8); PG8_WAIT_L(0); PG8_BAR; PG8_MMA(1, 0, At, B0); PG8_MMA(1, 1, At, B1); PG8_BAR; PG8_SCHED;
;             PG8_LDB(B0, 1, 0); PG8_LDB(B1, 1, 1); PG8_SCHED; PG8_LDA(At, 1, 0); PG8_STAGE(PG8_SA(0, 1), a2 + hstepA, voffA);
;             PG8_WAIT_V(8); PG8_WAIT_L(0); PG8_BAR; PG8_MMA(0, 0, At, B0); PG8_MMA(0, 1, At, B1); PG8_BAR; PG8_SCHED;
;             PG8_LDA(At, 1, 1); PG8_STAGE(PG8_SB(1, 0), b3, voffB); PG8_STAGE(PG8_SB(1, 1), b3 + hstepB, voffB); PG8_STAGE(PG8_SA(1, 0), a3, voffA);
;             PG8_WAIT_V(8); PG8_WAIT_L(0); PG8_BAR; PG8_MMA(1, 0, At, B0); PG8_MMA(1, 1, At, B1); PG8_BAR; PG8_SCHED;
	s_add_i32 s2, s2, s36
	v_lshl_add_u64 v[144:145], v[144:145], 0, s[94:95]
	s_mov_b32 m0, s2
	ds_read_b128 v[174:177], v149 offset:49152
	ds_read_b128 v[178:181], v149 offset:50176
	ds_read_b128 v[182:185], v149 offset:51200
	ds_read_b128 v[186:189], v149 offset:52224
	ds_read_b128 v[190:193], v149 offset:53248
	ds_read_b128 v[210:213], v149 offset:54272
	ds_read_b128 v[222:225], v149 offset:55296
	ds_read_b128 v[228:231], v149 offset:56320
	global_load_lds_dwordx4 v[144:145], off
	s_add_i32 m0, s2, 0x2000
	s_add_u32 s10, s10, 0x200080
	v_lshl_add_u64 v[144:145], v[194:195], 0, s[94:95]
	s_addc_u32 s11, s11, 0
	s_add_i32 s2, s33, s36
	global_load_lds_dwordx4 v[144:145], off
	v_lshl_add_u64 v[144:145], s[10:11], 0, v[0:1]
	s_mov_b32 m0, s2
	s_nop 0
	global_load_lds_dwordx4 v[144:145], off
	v_lshl_add_u64 v[144:145], s[10:11], 0, v[130:131]
	s_add_i32 m0, s2, 0x2000
	s_nop 0
	global_load_lds_dwordx4 v[144:145], off
	v_lshl_add_u64 v[144:145], v[214:215], 0, s[94:95]
	s_mov_b32 m0, s76
	s_nop 0
	global_load_lds_dwordx4 v[144:145], off
	v_lshl_add_u64 v[144:145], v[232:233], 0, s[94:95]
	s_mov_b32 m0, s77
	s_nop 0
	global_load_lds_dwordx4 v[144:145], off
	s_waitcnt vmcnt(8)
	s_waitcnt lgkmcnt(0)
	s_barrier
	s_setprio 1
	s_waitcnt lgkmcnt(0)
	v_mfma_f32_16x16x32_bf16 v[62:65], v[136:139], v[174:177], v[62:65]
	v_mfma_f32_16x16x32_bf16 v[62:65], v[140:143], v[178:181], v[62:65]
	v_mfma_f32_16x16x32_bf16 v[58:61], v[150:153], v[174:177], v[58:61]
	v_mfma_f32_16x16x32_bf16 v[58:61], v[154:157], v[178:181], v[58:61]
	v_mfma_f32_16x16x32_bf16 v[46:49], v[136:139], v[182:185], v[46:49]
	v_mfma_f32_16x16x32_bf16 v[46:49], v[140:143], v[186:189], v[46:49]
	v_mfma_f32_16x16x32_bf16 v[42:45], v[150:153], v[182:185], v[42:45]
	v_mfma_f32_16x16x32_bf16 v[42:45], v[154:157], v[186:189], v[42:45]
	v_mfma_f32_16x16x32_bf16 v[30:33], v[136:139], v[190:193], v[30:33]
	v_mfma_f32_16x16x32_bf16 v[30:33], v[140:143], v[210:213], v[30:33]
	v_mfma_f32_16x16x32_bf16 v[26:29], v[150:153], v[190:193], v[26:29]
	v_mfma_f32_16x16x32_bf16 v[26:29], v[154:157], v[210:213], v[26:29]
	v_mfma_f32_16x16x32_bf16 v[14:17], v[136:139], v[222:225], v[14:17]
	v_mfma_f32_16x16x32_bf16 v[14:17], v[140:143], v[228:231], v[14:17]
	v_mfma_f32_16x16x32_bf16 v[10:13], v[150:153], v[222:225], v[10:13]
	v_mfma_f32_16x16x32_bf16 v[10:13], v[154:157], v[228:231], v[10:13]
	s_setprio 0
	s_setprio 1
	v_mfma_f32_16x16x32_bf16 v[54:57], v[158:161], v[174:177], v[54:57]
	v_mfma_f32_16x16x32_bf16 v[54:57], v[162:165], v[178:181], v[54:57]
	v_mfma_f32_16x16x32_bf16 v[50:53], v[166:169], v[174:177], v[50:53]
	v_mfma_f32_16x16x32_bf16 v[50:53], v[170:173], v[178:181], v[50:53]
	v_mfma_f32_16x16x32_bf16 v[38:41], v[158:161], v[182:185], v[38:41]
	v_mfma_f32_16x16x32_bf16 v[38:41], v[162:165], v[186:189], v[38:41]
	v_mfma_f32_16x16x32_bf16 v[34:37], v[166:169], v[182:185], v[34:37]
	v_mfma_f32_16x16x32_bf16 v[34:37], v[170:173], v[186:189], v[34:37]
	v_mfma_f32_16x16x32_bf16 v[22:25], v[158:161], v[190:193], v[22:25]
	v_mfma_f32_16x16x32_bf16 v[22:25], v[162:165], v[210:213], v[22:25]
	v_mfma_f32_16x16x32_bf16 v[18:21], v[166:169], v[190:193], v[18:21]
	v_mfma_f32_16x16x32_bf16 v[18:21], v[170:173], v[210:213], v[18:21]
	v_mfma_f32_16x16x32_bf16 v[6:9], v[158:161], v[222:225], v[6:9]
	v_mfma_f32_16x16x32_bf16 v[6:9], v[162:165], v[228:231], v[6:9]
	v_mfma_f32_16x16x32_bf16 v[2:5], v[166:169], v[222:225], v[2:5]
	v_mfma_f32_16x16x32_bf16 v[2:5], v[170:173], v[228:231], v[2:5]
	s_setprio 0
	s_barrier
	s_add_i32 vcc_lo, vcc_lo, 2
	s_add_u32 s8, s8, 0x100
	s_addc_u32 s9, s9, 0
	s_add_u32 s91, s91, 0x100
	s_addc_u32 s93, s93, 0
	s_cmpk_gt_u32 vcc_lo, 0x7d
	s_cbranch_scc0 .LBB0_297
	s_and_b64 vcc, exec, s[42:43]
	s_cbranch_vccz .LBB0_300
	s_barrier

; #define PG8_STAGE(bufoff, gbase, voff) do { _Pragma("unroll") for (int _i = 0; _i < 2; ++_i) \
;         __builtin_amdgcn_global_load_lds((const unsigned*)((const char*)(gbase) + (voff)[_i]), (PG8_LAS unsigned*)(lds + (bufoff) + ldsw + _i * 8192), 16, 0, 0); } while (0)
; #define PG8_LDA(dst, b, h) do { _Pragma("unroll") for (int m = 0; m < 4; ++m) _Pragma("unroll") for (int k = 0; k < 2; ++k) dst[m][k] = *(const PG8_LAS bf16x8*)(lds + PG8_SA(b, h) + aoff + m * 2048 + k * 1024); } while (0)
; #define PG8_LDB(dst, b, h) do { _Pragma("unroll") for (int n = 0; n < 2; ++n) _Pragma("unroll") for (int k = 0; k < 2; ++k) dst[n][k] = *(const PG8_LAS bf16x8*)(lds + PG8_SB(b, h) + boff + n * 2048 + k * 1024); } while (0)
; #define PG8_MMA(ai, bj, At, Bt) do { __builtin_amdgcn_s_setprio(1); _Pragma("unroll") for (int m = 0; m < 4; ++m) _Pragma("unroll") for (int n = 0; n < 2; ++n) _Pragma("unroll") for (int k = 0; k < 2; ++k) \
;         acc[ai][bj][m][n] = __builtin_amdgcn_mfma_f32_16x16x32_bf16(Bt[n][k], At[m][k], acc[ai][bj][m][n], 0, 0, 0); __builtin_amdgcn_s_setprio(0); } while (0)
; #define PG8_WAIT_V(n) asm volatile("s_waitcnt vmcnt(" #n ")" ::: "memory")
; template <class Epi, class Sched, bool ALIGN_EPI = false, bool SP2 = false>
; __device__ __forceinline__ void gemm_phase(PG8_LAS unsigned char* lds, const Gemm g, const Sched& S, const Epi& E) {
;     ...
;             PG8_LDB(B0, 0, 0); PG8_LDB(B1, 0, 1); PG8_SCHED; PG8_LDA(At, 0, 0); PG8_STAGE(PG8_SA(1, 1), a1 + hstepA, voffA);
;             PG8_WAIT_V(8); PG8_WAIT_L(0); PG8_BAR; PG8_MMA(0, 0, At, B0); PG8_MMA(0, 1, At, B1); PG8_BAR; PG8_SCHED;
;             PG8_LDA(At, 0, 1); PG8_STAGE(PG8_SB(0, 0), b2, voffB); PG8_STAGE(PG8_SB(0, 1), b2 + hstepB, voffB); PG8_STAGE(PG8_SA(0, 0), a2, voffA);
;             PG8_WAIT_V(8); PG8_WAIT_L(0); PG8_BAR; PG8_MMA(1, 0, At, B0); PG8_MMA(1, 1, At, B1); PG8_BAR; PG8_SCHED;
;             PG8_LDB(B0, 1, 0); PG8_LDB(B1, 1, 1); PG8_SCHED; PG8_LDA(At, 1, 0); PG8_STAGE(PG8_SA(0, 1), a2 + hstepA, voffA);
;             PG8_WAIT_V(8); PG8_WAIT_L(0); PG8_BAR; PG8_MMA(0, 0, At, B0); PG8_MMA(0, 1, At, B1); PG8_BAR; PG8_SCHED;
;             PG8_LDA(At, 1, 1); PG8_STAGE(PG8_SB(1, 0), b3, voffB); PG8_STAGE(PG8_SB(1, 1), b3 + hstepB, voffB); PG8_STAGE(PG8_SA(1, 0), a3, voffA);
;             PG8_WAIT_V(8); PG8_WAIT_L(0); PG8_BAR; PG8_MMA(1, 0, At, B0); PG8_MMA(1, 1, At, B1); PG8_BAR; PG8_SCHED;
.LBB0_415:
	s_add_u32 s2, s6, 0xfff80080
	s_addc_u32 s33, s7, -1
	s_add_i32 s68, s17, 0x100
	s_cmp_eq_u32 s72, 28
	s_cselect_b32 s47, s39, s33
	s_cselect_b32 s46, s62, s2
	v_add_u32_e32 v144, s68, v147
	s_cselect_b32 s45, s27, s70
	s_cselect_b32 s44, s63, s65
	s_add_i32 s2, s24, 0x100
	ds_read_b128 v[140:143], v144
	ds_read_b128 v[150:153], v144 offset:1024
	ds_read_b128 v[154:157], v144 offset:2048
	ds_read_b128 v[158:161], v144 offset:3072
	v_add_u32_e32 v144, s2, v147
	ds_read_b128 v[162:165], v144
	ds_read_b128 v[166:169], v144 offset:1024
	ds_read_b128 v[170:173], v144 offset:2048
	ds_read_b128 v[174:177], v144 offset:3072
	v_lshl_add_u64 v[194:195], s[6:7], 0, v[136:137]
	s_add_i32 m0, s50, 0xc000
	ds_read_b128 v[178:181], v149
	ds_read_b128 v[182:185], v149 offset:1024
	ds_read_b128 v[186:189], v149 offset:2048
	ds_read_b128 v[190:193], v149 offset:3072
	ds_read_b128 v[210:213], v149 offset:4096
	ds_read_b128 v[222:225], v149 offset:5120
	ds_read_b128 v[228:231], v149 offset:6144
	ds_read_b128 v[232:235], v149 offset:7168
	global_load_lds_dwordx4 v[194:195], off
	v_lshl_add_u64 v[194:195], s[6:7], 0, v[138:139]
	s_add_i32 m0, s50, 0xe000
	s_nop 0
	global_load_lds_dwordx4 v[194:195], off
	s_waitcnt vmcnt(8)
	s_waitcnt lgkmcnt(0)
	s_barrier
	s_setprio 1
	s_waitcnt lgkmcnt(0)
	v_mfma_f32_16x16x32_bf16 v[126:129], v[140:143], v[178:181], v[126:129]
	v_mfma_f32_16x16x32_bf16 v[126:129], v[150:153], v[182:185], v[126:129]
	v_mfma_f32_16x16x32_bf16 v[122:125], v[154:157], v[178:181], v[122:125]
	v_mfma_f32_16x16x32_bf16 v[122:125], v[158:161], v[182:185], v[122:125]
	v_mfma_f32_16x16x32_bf16 v[110:113], v[140:143], v[186:189], v[110:113]
	v_mfma_f32_16x16x32_bf16 v[110:113], v[150:153], v[190:193], v[110:113]
	v_mfma_f32_16x16x32_bf16 v[106:109], v[154:157], v[186:189], v[106:109]
	v_mfma_f32_16x16x32_bf16 v[106:109], v[158:161], v[190:193], v[106:109]
	v_mfma_f32_16x16x32_bf16 v[94:97], v[140:143], v[210:213], v[94:97]
	v_mfma_f32_16x16x32_bf16 v[94:97], v[150:153], v[222:225], v[94:97]
	v_mfma_f32_16x16x32_bf16 v[90:93], v[154:157], v[210:213], v[90:93]
	v_mfma_f32_16x16x32_bf16 v[90:93], v[158:161], v[222:225], v[90:93]
	v_mfma_f32_16x16x32_bf16 v[78:81], v[140:143], v[228:231], v[78:81]
	v_mfma_f32_16x16x32_bf16 v[78:81], v[150:153], v[232:235], v[78:81]
	v_mfma_f32_16x16x32_bf16 v[74:77], v[154:157], v[228:231], v[74:77]
	v_mfma_f32_16x16x32_bf16 v[74:77], v[158:161], v[232:235], v[74:77]
	s_setprio 0
	s_setprio 1
	v_mfma_f32_16x16x32_bf16 v[118:121], v[162:165], v[178:181], v[118:121]
	v_mfma_f32_16x16x32_bf16 v[118:121], v[166:169], v[182:185], v[118:121]
	v_mfma_f32_16x16x32_bf16 v[114:117], v[170:173], v[178:181], v[114:117]
	v_mfma_f32_16x16x32_bf16 v[114:117], v[174:177], v[182:185], v[114:117]
	v_mfma_f32_16x16x32_bf16 v[102:105], v[162:165], v[186:189], v[102:105]
	v_mfma_f32_16x16x32_bf16 v[102:105], v[166:169], v[190:193], v[102:105]
	v_mfma_f32_16x16x32_bf16 v[98:101], v[170:173], v[186:189], v[98:101]
	v_mfma_f32_16x16x32_bf16 v[98:101], v[174:177], v[190:193], v[98:101]
	v_mfma_f32_16x16x32_bf16 v[86:89], v[162:165], v[210:213], v[86:89]
	v_mfma_f32_16x16x32_bf16 v[86:89], v[166:169], v[222:225], v[86:89]
	v_mfma_f32_16x16x32_bf16 v[82:85], v[170:173], v[210:213], v[82:85]
	v_mfma_f32_16x16x32_bf16 v[82:85], v[174:177], v[222:225], v[82:85]
	v_mfma_f32_16x16x32_bf16 v[70:73], v[162:165], v[228:231], v[70:73]
	v_mfma_f32_16x16x32_bf16 v[70:73], v[166:169], v[232:235], v[70:73]
	v_mfma_f32_16x16x32_bf16 v[66:69], v[170:173], v[228:231], v[66:69]
	v_mfma_f32_16x16x32_bf16 v[66:69], v[174:177], v[232:235], v[66:69]
	s_setprio 0
	s_barrier
	s_add_i32 s33, s68, s49
	v_lshl_add_u64 v[194:195], s[44:45], 0, v[0:1]
	s_mov_b32 m0, s33
	ds_read_b128 v[178:181], v149 offset:16384
	ds_read_b128 v[182:185], v149 offset:17408
	ds_read_b128 v[186:189], v149 offset:18432
	ds_read_b128 v[190:193], v149 offset:19456
	ds_read_b128 v[210:213], v149 offset:20480
	ds_read_b128 v[222:225], v149 offset:21504
	ds_read_b128 v[228:231], v149 offset:22528
	ds_read_b128 v[232:235], v149 offset:23552
	global_load_lds_dwordx4 v[194:195], off
	s_add_i32 m0, s33, 0x2000
	s_add_u32 s76, s44, 0x80000
	v_lshl_add_u64 v[214:215], s[44:45], 0, v[130:131]
	s_addc_u32 s77, s45, 0
	s_add_i32 s2, s2, s49
	global_load_lds_dwordx4 v[214:215], off
	v_lshl_add_u64 v[236:237], s[76:77], 0, v[0:1]
	s_mov_b32 m0, s2
	v_lshl_add_u64 v[238:239], s[46:47], 0, v[132:133]
	global_load_lds_dwordx4 v[236:237], off
	v_lshl_add_u64 v[236:237], s[76:77], 0, v[130:131]
	s_add_i32 m0, s2, 0x2000
	s_nop 0
	global_load_lds_dwordx4 v[236:237], off
	v_lshl_add_u64 v[236:237], s[46:47], 0, v[134:135]
	s_mov_b32 m0, s50
	s_nop 0
	global_load_lds_dwordx4 v[236:237], off
	s_mov_b32 m0, s51
	s_nop 0
	global_load_lds_dwordx4 v[238:239], off
	s_waitcnt vmcnt(8)
	s_waitcnt lgkmcnt(0)
	s_barrier
; #define PG8_STAGE(bufoff, gbase, voff) do { _Pragma("unroll") for (int _i = 0; _i < 2; ++_i) \
;         __builtin_amdgcn_global_load_lds((const unsigned*)((const char*)(gbase) + (voff)[_i]), (PG8_LAS unsigned*)(lds + (bufoff) + ldsw + _i * 8192), 16, 0, 0); } while (0)
; #define PG8_LDA(dst, b, h) do { _Pragma("unroll") for (int m = 0; m < 4; ++m) _Pragma("unroll") for (int k = 0; k < 2; ++k) dst[m][k] = *(const PG8_LAS bf16x8*)(lds + PG8_SA(b, h) + aoff + m * 2048 + k * 1024); } while (0)
; #define PG8_LDB(dst, b, h) do { _Pragma("unroll") for (int n = 0; n < 2; ++n) _Pragma("unroll") for (int k = 0; k < 2; ++k) dst[n][k] = *(const PG8_LAS bf16x8*)(lds + PG8_SB(b, h) + boff + n * 2048 + k * 1024); } while (0)
; #define PG8_MMA(ai, bj, At, Bt) do { __builtin_amdgcn_s_setprio(1); _Pragma("unroll") for (int m = 0; m < 4; ++m) _Pragma("unroll") for (int n = 0; n < 2; ++n) _Pragma("unroll") for (int k = 0; k < 2; ++k) \
;         acc[ai][bj][m][n] = __builtin_amdgcn_mfma_f32_16x16x32_bf16(Bt[n][k], At[m][k], acc[ai][bj][m][n], 0, 0, 0); __builtin_amdgcn_s_setprio(0); } while (0)
; #define PG8_WAIT_V(n) asm volatile("s_waitcnt vmcnt(" #n ")" ::: "memory")
; #define PG8_WAIT_L(n) asm volatile("s_waitcnt lgkmcnt(" #n ")" ::: "memory")
; #define PG8_BAR __builtin_amdgcn_s_barrier()
; #define PG8_SCHED __builtin_amdgcn_sched_barrier(0)
; template <class Epi, class Sched, bool ALIGN_EPI = false, bool SP2 = false>
; __device__ __forceinline__ void gemm_phase(PG8_LAS unsigned char* lds, const Gemm g, const Sched& S, const Epi& E) {
;     ...
;             PG8_WAIT_V(8); PG8_WAIT_L(0); PG8_BAR; PG8_MMA(1, 0, At, B0); PG8_MMA(1, 1, At, B1); PG8_BAR; PG8_SCHED;
;             PG8_LDB(B0, 1, 0); PG8_LDB(B1, 1, 1); PG8_SCHED; PG8_LDA(At, 1, 0); PG8_STAGE(PG8_SA(0, 1), a2 + hstepA, voffA);
;             PG8_WAIT_V(8); PG8_WAIT_L(0); PG8_BAR; PG8_MMA(0, 0, At, B0); PG8_MMA(0, 1, At, B1); PG8_BAR; PG8_SCHED;
	s_setprio 1
	s_waitcnt lgkmcnt(0)
	v_mfma_f32_16x16x32_bf16 v[62:65], v[140:143], v[178:181], v[62:65]
	v_mfma_f32_16x16x32_bf16 v[62:65], v[150:153], v[182:185], v[62:65]
	v_mfma_f32_16x16x32_bf16 v[58:61], v[154:157], v[178:181], v[58:61]
	v_mfma_f32_16x16x32_bf16 v[58:61], v[158:161], v[182:185], v[58:61]
	v_mfma_f32_16x16x32_bf16 v[46:49], v[140:143], v[186:189], v[46:49]
	v_mfma_f32_16x16x32_bf16 v[46:49], v[150:153], v[190:193], v[46:49]
	v_mfma_f32_16x16x32_bf16 v[42:45], v[154:157], v[186:189], v[42:45]
	v_mfma_f32_16x16x32_bf16 v[42:45], v[158:161], v[190:193], v[42:45]
	v_mfma_f32_16x16x32_bf16 v[30:33], v[140:143], v[210:213], v[30:33]
	v_mfma_f32_16x16x32_bf16 v[30:33], v[150:153], v[222:225], v[30:33]
	v_mfma_f32_16x16x32_bf16 v[26:29], v[154:157], v[210:213], v[26:29]
	v_mfma_f32_16x16x32_bf16 v[26:29], v[158:161], v[222:225], v[26:29]
	v_mfma_f32_16x16x32_bf16 v[14:17], v[140:143], v[228:231], v[14:17]
	v_mfma_f32_16x16x32_bf16 v[14:17], v[150:153], v[232:235], v[14:17]
	v_mfma_f32_16x16x32_bf16 v[10:13], v[154:157], v[228:231], v[10:13]
	v_mfma_f32_16x16x32_bf16 v[10:13], v[158:161], v[232:235], v[10:13]
	s_setprio 0
	s_setprio 1
	v_mfma_f32_16x16x32_bf16 v[54:57], v[162:165], v[178:181], v[54:57]
	v_mfma_f32_16x16x32_bf16 v[54:57], v[166:169], v[182:185], v[54:57]
	v_mfma_f32_16x16x32_bf16 v[50:53], v[170:173], v[178:181], v[50:53]
	v_mfma_f32_16x16x32_bf16 v[50:53], v[174:177], v[182:185], v[50:53]
	v_mfma_f32_16x16x32_bf16 v[38:41], v[162:165], v[186:189], v[38:41]
	v_mfma_f32_16x16x32_bf16 v[38:41], v[166:169], v[190:193], v[38:41]
	v_mfma_f32_16x16x32_bf16 v[34:37], v[170:173], v[186:189], v[34:37]
	v_mfma_f32_16x16x32_bf16 v[34:37], v[174:177], v[190:193], v[34:37]
	v_mfma_f32_16x16x32_bf16 v[22:25], v[162:165], v[210:213], v[22:25]
	v_mfma_f32_16x16x32_bf16 v[22:25], v[166:169], v[222:225], v[22:25]
	v_mfma_f32_16x16x32_bf16 v[18:21], v[170:173], v[210:213], v[18:21]
	v_mfma_f32_16x16x32_bf16 v[18:21], v[174:177], v[222:225], v[18:21]
	v_mfma_f32_16x16x32_bf16 v[6:9], v[162:165], v[228:231], v[6:9]
	v_mfma_f32_16x16x32_bf16 v[6:9], v[166:169], v[232:235], v[6:9]
	v_mfma_f32_16x16x32_bf16 v[2:5], v[170:173], v[228:231], v[2:5]
	v_mfma_f32_16x16x32_bf16 v[2:5], v[174:177], v[232:235], v[2:5]
	s_setprio 0
	s_barrier
	s_add_i32 s2, s87, 0x100
	v_add_u32_e32 v144, s2, v147
	s_add_i32 s33, s69, 0x100
	ds_read_b128 v[140:143], v144
	ds_read_b128 v[150:153], v144 offset:1024
	ds_read_b128 v[154:157], v144 offset:2048
	ds_read_b128 v[158:161], v144 offset:3072
	v_add_u32_e32 v144, s33, v147
	ds_read_b128 v[162:165], v144
	ds_read_b128 v[166:169], v144 offset:1024
	ds_read_b128 v[170:173], v144 offset:2048
	ds_read_b128 v[174:177], v144 offset:3072
	s_add_u32 s46, s46, 0x80000
	s_addc_u32 s47, s47, 0
	s_mov_b32 m0, s57
	v_lshl_add_u64 v[240:241], s[46:47], 0, v[134:135]
	ds_read_b128 v[178:181], v149 offset:32768
	ds_read_b128 v[182:185], v149 offset:33792
	ds_read_b128 v[186:189], v149 offset:34816
	ds_read_b128 v[190:193], v149 offset:35840
	ds_read_b128 v[210:213], v149 offset:36864
	ds_read_b128 v[222:225], v149 offset:37888
	ds_read_b128 v[228:231], v149 offset:38912
	ds_read_b128 v[232:235], v149 offset:39936
	global_load_lds_dwordx4 v[240:241], off
	v_lshl_add_u64 v[240:241], s[46:47], 0, v[132:133]
	s_mov_b32 m0, s58
	s_nop 0
	global_load_lds_dwordx4 v[240:241], off
	s_waitcnt vmcnt(8)
	s_waitcnt lgkmcnt(0)
	s_barrier
	s_setprio 1
	s_waitcnt lgkmcnt(0)
	v_mfma_f32_16x16x32_bf16 v[126:129], v[140:143], v[178:181], v[126:129]
	v_mfma_f32_16x16x32_bf16 v[126:129], v[150:153], v[182:185], v[126:129]
	v_mfma_f32_16x16x32_bf16 v[122:125], v[154:157], v[178:181], v[122:125]
	v_mfma_f32_16x16x32_bf16 v[122:125], v[158:161], v[182:185], v[122:125]
	v_mfma_f32_16x16x32_bf16 v[110:113], v[140:143], v[186:189], v[110:113]
	v_mfma_f32_16x16x32_bf16 v[110:113], v[150:153], v[190:193], v[110:113]
	v_mfma_f32_16x16x32_bf16 v[106:109], v[154:157], v[186:189], v[106:109]
	v_mfma_f32_16x16x32_bf16 v[106:109], v[158:161], v[190:193], v[106:109]
	v_mfma_f32_16x16x32_bf16 v[94:97], v[140:143], v[210:213], v[94:97]
	v_mfma_f32_16x16x32_bf16 v[94:97], v[150:153], v[222:225], v[94:97]
	v_mfma_f32_16x16x32_bf16 v[90:93], v[154:157], v[210:213], v[90:93]
	v_mfma_f32_16x16x32_bf16 v[90:93], v[158:161], v[222:225], v[90:93]
	v_mfma_f32_16x16x32_bf16 v[78:81], v[140:143], v[228:231], v[78:81]
	v_mfma_f32_16x16x32_bf16 v[78:81], v[150:153], v[232:235], v[78:81]
	v_mfma_f32_16x16x32_bf16 v[74:77], v[154:157], v[228:231], v[74:77]
	v_mfma_f32_16x16x32_bf16 v[74:77], v[158:161], v[232:235], v[74:77]
	s_setprio 0
	s_setprio 1
	v_mfma_f32_16x16x32_bf16 v[118:121], v[162:165], v[178:181], v[118:121]
	v_mfma_f32_16x16x32_bf16 v[118:121], v[166:169], v[182:185], v[118:121]
	v_mfma_f32_16x16x32_bf16 v[114:117], v[170:173], v[178:181], v[114:117]
	v_mfma_f32_16x16x32_bf16 v[114:117], v[174:177], v[182:185], v[114:117]
	v_mfma_f32_16x16x32_bf16 v[102:105], v[162:165], v[186:189], v[102:105]
	v_mfma_f32_16x16x32_bf16 v[102:105], v[166:169], v[190:193], v[102:105]
	v_mfma_f32_16x16x32_bf16 v[98:101], v[170:173], v[186:189], v[98:101]
	v_mfma_f32_16x16x32_bf16 v[98:101], v[174:177], v[190:193], v[98:101]
	v_mfma_f32_16x16x32_bf16 v[86:89], v[162:165], v[210:213], v[86:89]
	v_mfma_f32_16x16x32_bf16 v[86:89], v[166:169], v[222:225], v[86:89]
	v_mfma_f32_16x16x32_bf16 v[82:85], v[170:173], v[210:213], v[82:85]
	v_mfma_f32_16x16x32_bf16 v[82:85], v[174:177], v[222:225], v[82:85]
	v_mfma_f32_16x16x32_bf16 v[70:73], v[162:165], v[228:231], v[70:73]
	v_mfma_f32_16x16x32_bf16 v[70:73], v[166:169], v[232:235], v[70:73]
	v_mfma_f32_16x16x32_bf16 v[66:69], v[170:173], v[228:231], v[66:69]
	v_mfma_f32_16x16x32_bf16 v[66:69], v[174:177], v[232:235], v[66:69]
	s_setprio 0
	s_barrier
; #define PG8_STAGE(bufoff, gbase, voff) do { _Pragma("unroll") for (int _i = 0; _i < 2; ++_i) \
;         __builtin_amdgcn_global_load_lds((const unsigned*)((const char*)(gbase) + (voff)[_i]), (PG8_LAS unsigned*)(lds + (bufoff) + ldsw + _i * 8192), 16, 0, 0); } while (0)
; #define PG8_LDA(dst, b, h) do { _Pragma("unroll") for (int m = 0; m < 4; ++m) _Pragma("unroll") for (int k = 0; k < 2; ++k) dst[m][k] = *(const PG8_LAS bf16x8*)(lds + PG8_SA(b, h) + aoff + m * 2048 + k * 1024); } while (0)
; #define PG8_MMA(ai, bj, At, Bt) do { __builtin_amdgcn_s_setprio(1); _Pragma("unroll") for (int m = 0; m < 4; ++m) _Pragma("unroll") for (int n = 0; n < 2; ++n) _Pragma("unroll") for (int k = 0; k < 2; ++k) \
;         acc[ai][bj][m][n] = __builtin_amdgcn_mfma_f32_16x16x32_bf16(Bt[n][k], At[m][k], acc[ai][bj][m][n], 0, 0, 0); __builtin_amdgcn_s_setprio(0); } while (0)
; #define PG8_WAIT_V(n) asm volatile("s_waitcnt vmcnt(" #n ")" ::: "memory")
; #define PG8_WAIT_L(n) asm volatile("s_waitcnt lgkmcnt(" #n ")" ::: "memory")
; #define PG8_BAR __builtin_amdgcn_s_barrier()
; #define PG8_SCHED __builtin_amdgcn_sched_barrier(0)
; template <class Epi, class Sched, bool ALIGN_EPI = false, bool SP2 = false>
; __device__ __forceinline__ void gemm_phase(PG8_LAS unsigned char* lds, const Gemm g, const Sched& S, const Epi& E) {
;     ...
;             PG8_LDA(At, 1, 1); PG8_STAGE(PG8_SB(1, 0), b3, voffB); PG8_STAGE(PG8_SB(1, 1), b3 + hstepB, voffB); PG8_STAGE(PG8_SA(1, 0), a3, voffA);
;             PG8_WAIT_V(8); PG8_WAIT_L(0); PG8_BAR; PG8_MMA(1, 0, At, B0); PG8_MMA(1, 1, At, B1); PG8_BAR; PG8_SCHED;
	s_add_i32 s2, s2, s49
	v_lshl_add_u64 v[194:195], v[194:195], 0, s[94:95]
	s_mov_b32 m0, s2
	ds_read_b128 v[178:181], v149 offset:49152
	ds_read_b128 v[182:185], v149 offset:50176
	ds_read_b128 v[186:189], v149 offset:51200
	ds_read_b128 v[190:193], v149 offset:52224
	ds_read_b128 v[210:213], v149 offset:53248
	ds_read_b128 v[222:225], v149 offset:54272
	ds_read_b128 v[228:231], v149 offset:55296
	ds_read_b128 v[232:235], v149 offset:56320
	global_load_lds_dwordx4 v[194:195], off
	s_add_i32 m0, s2, 0x2000
	s_add_u32 s44, s44, 0x80080
	v_lshl_add_u64 v[194:195], v[214:215], 0, s[94:95]
	s_addc_u32 s45, s45, 0
	s_add_i32 s2, s33, s49
	global_load_lds_dwordx4 v[194:195], off
	v_lshl_add_u64 v[194:195], s[44:45], 0, v[0:1]
	s_mov_b32 m0, s2
	s_nop 0
	global_load_lds_dwordx4 v[194:195], off
	v_lshl_add_u64 v[194:195], s[44:45], 0, v[130:131]
	s_add_i32 m0, s2, 0x2000
	s_nop 0
	global_load_lds_dwordx4 v[194:195], off
	v_lshl_add_u64 v[194:195], v[236:237], 0, s[94:95]
	s_mov_b32 m0, s59
	s_nop 0
	global_load_lds_dwordx4 v[194:195], off
	v_lshl_add_u64 v[194:195], v[238:239], 0, s[94:95]
	s_mov_b32 m0, s60
	s_nop 0
	global_load_lds_dwordx4 v[194:195], off
	s_waitcnt vmcnt(8)
	s_waitcnt lgkmcnt(0)
	s_barrier
	s_setprio 1
	s_waitcnt lgkmcnt(0)
	v_mfma_f32_16x16x32_bf16 v[62:65], v[140:143], v[178:181], v[62:65]
	v_mfma_f32_16x16x32_bf16 v[62:65], v[150:153], v[182:185], v[62:65]
	v_mfma_f32_16x16x32_bf16 v[58:61], v[154:157], v[178:181], v[58:61]
	v_mfma_f32_16x16x32_bf16 v[58:61], v[158:161], v[182:185], v[58:61]
	v_mfma_f32_16x16x32_bf16 v[46:49], v[140:143], v[186:189], v[46:49]
	v_mfma_f32_16x16x32_bf16 v[46:49], v[150:153], v[190:193], v[46:49]
	v_mfma_f32_16x16x32_bf16 v[42:45], v[154:157], v[186:189], v[42:45]
	v_mfma_f32_16x16x32_bf16 v[42:45], v[158:161], v[190:193], v[42:45]
	v_mfma_f32_16x16x32_bf16 v[30:33], v[140:143], v[210:213], v[30:33]
	v_mfma_f32_16x16x32_bf16 v[30:33], v[150:153], v[222:225], v[30:33]
	v_mfma_f32_16x16x32_bf16 v[26:29], v[154:157], v[210:213], v[26:29]
	v_mfma_f32_16x16x32_bf16 v[26:29], v[158:161], v[222:225], v[26:29]
	v_mfma_f32_16x16x32_bf16 v[14:17], v[140:143], v[228:231], v[14:17]
	v_mfma_f32_16x16x32_bf16 v[14:17], v[150:153], v[232:235], v[14:17]
	v_mfma_f32_16x16x32_bf16 v[10:13], v[154:157], v[228:231], v[10:13]
	v_mfma_f32_16x16x32_bf16 v[10:13], v[158:161], v[232:235], v[10:13]
	s_setprio 0
	s_setprio 1
	v_mfma_f32_16x16x32_bf16 v[54:57], v[162:165], v[178:181], v[54:57]
	v_mfma_f32_16x16x32_bf16 v[54:57], v[166:169], v[182:185], v[54:57]
	v_mfma_f32_16x16x32_bf16 v[50:53], v[170:173], v[178:181], v[50:53]
	v_mfma_f32_16x16x32_bf16 v[50:53], v[174:177], v[182:185], v[50:53]
	v_mfma_f32_16x16x32_bf16 v[38:41], v[162:165], v[186:189], v[38:41]
	v_mfma_f32_16x16x32_bf16 v[38:41], v[166:169], v[190:193], v[38:41]
	v_mfma_f32_16x16x32_bf16 v[34:37], v[170:173], v[186:189], v[34:37]
	v_mfma_f32_16x16x32_bf16 v[34:37], v[174:177], v[190:193], v[34:37]
	v_mfma_f32_16x16x32_bf16 v[22:25], v[162:165], v[210:213], v[22:25]
	v_mfma_f32_16x16x32_bf16 v[22:25], v[166:169], v[222:225], v[22:25]
	v_mfma_f32_16x16x32_bf16 v[18:21], v[170:173], v[210:213], v[18:21]
	v_mfma_f32_16x16x32_bf16 v[18:21], v[174:177], v[222:225], v[18:21]
	v_mfma_f32_16x16x32_bf16 v[6:9], v[162:165], v[228:231], v[6:9]
	v_mfma_f32_16x16x32_bf16 v[6:9], v[166:169], v[232:235], v[6:9]
	v_mfma_f32_16x16x32_bf16 v[2:5], v[170:173], v[228:231], v[2:5]
	v_mfma_f32_16x16x32_bf16 v[2:5], v[174:177], v[232:235], v[2:5]
	s_setprio 0
	s_barrier
	s_add_i32 s72, s72, 2
	s_add_u32 s6, s6, 0x100
	s_addc_u32 s7, s7, 0
	s_add_u32 s65, s65, 0x100
	s_addc_u32 s70, s70, 0
	s_cmp_gt_u32 s72, 29
	s_cbranch_scc0 .LBB0_415
	s_and_b64 vcc, exec, s[14:15]
	s_cbranch_vccz .LBB0_418
	s_barrier

; #define PG8_STAGE(bufoff, gbase, voff) do { _Pragma("unroll") for (int _i = 0; _i < 2; ++_i) \
;         __builtin_amdgcn_global_load_lds((const unsigned*)((const char*)(gbase) + (voff)[_i]), (PG8_LAS unsigned*)(lds + (bufoff) + ldsw + _i * 8192), 16, 0, 0); } while (0)
; #define PG8_LDA(dst, b, h) do { _Pragma("unroll") for (int m = 0; m < 4; ++m) _Pragma("unroll") for (int k = 0; k < 2; ++k) dst[m][k] = *(const PG8_LAS bf16x8*)(lds + PG8_SA(b, h) + aoff + m * 2048 + k * 1024); } while (0)
; #define PG8_LDB(dst, b, h) do { _Pragma("unroll") for (int n = 0; n < 2; ++n) _Pragma("unroll") for (int k = 0; k < 2; ++k) dst[n][k] = *(const PG8_LAS bf16x8*)(lds + PG8_SB(b, h) + boff + n * 2048 + k * 1024); } while (0)
; #define PG8_MMA(ai, bj, At, Bt) do { __builtin_amdgcn_s_setprio(1); _Pragma("unroll") for (int m = 0; m < 4; ++m) _Pragma("unroll") for (int n = 0; n < 2; ++n) _Pragma("unroll") for (int k = 0; k < 2; ++k) \
;         acc[ai][bj][m][n] = __builtin_amdgcn_mfma_f32_16x16x32_bf16(Bt[n][k], At[m][k], acc[ai][bj][m][n], 0, 0, 0); __builtin_amdgcn_s_setprio(0); } while (0)
; #define PG8_WAIT_V(n) asm volatile("s_waitcnt vmcnt(" #n ")" ::: "memory")
; #define PG8_WAIT_L(n) asm volatile("s_waitcnt lgkmcnt(" #n ")" ::: "memory")
; #define PG8_BAR __builtin_amdgcn_s_barrier()
; #define PG8_SCHED __builtin_amdgcn_sched_barrier(0)
; template <class Epi, class Sched, bool ALIGN_EPI = false, bool SP2 = false>
; __device__ __forceinline__ void gemm_phase(PG8_LAS unsigned char* lds, const Gemm g, const Sched& S, const Epi& E) {
;     ...
;             const bool last = (t == nt - 2);
;             const char* a1 = cA + (size_t)(t + 1) * kstep;
;             const char* a2 = last ? nA : cA + (size_t)(t + 2) * kstep; const char* b2 = last ? nB : cB + (size_t)(t + 2) * kstep;
;             const char* a3 = a2 + kstep; const char* b3 = b2 + kstep;
;             if (last && has_next) S.a_ready(nxt);
;             if constexpr (SP2) {
;             PG8_LDB(B0, 0, 0); PG8_LDB(B1, 0, 1); PG8_SCHED; PG8_LDA(At, 0, 0); PG8_STAGE(PG8_SA(1, 1), a1 + hstepA, voffA);
;             PG8_WAIT_V(8); PG8_WAIT_L(0); PG8_BAR; PG8_MMA(0, 0, At, B0); PG8_MMA(0, 1, At, B1); PG8_BAR; PG8_SCHED;
;             PG8_LDA(At, 0, 1); PG8_STAGE(PG8_SB(0, 0), b2, voffB); PG8_STAGE(PG8_SB(0, 1), b2 + hstepB, voffB); PG8_STAGE(PG8_SA(0, 0), a2, voffA);
.LBB0_456:
	s_add_u32 s2, s8, 0xfff80080
	s_addc_u32 s10, s9, -1
	s_add_i32 s33, s17, 0x100
	s_cmp_eq_u32 s91, 28
	s_cselect_b32 s59, s47, s10
	s_cselect_b32 s58, s57, s2
	v_add_u32_e32 v144, s33, v147
	s_cselect_b32 s11, s45, s83
	s_cselect_b32 s10, s70, s74
	s_add_i32 s2, s24, 0x100
	ds_read_b128 v[136:139], v144
	ds_read_b128 v[140:143], v144 offset:1024
	ds_read_b128 v[150:153], v144 offset:2048
	ds_read_b128 v[154:157], v144 offset:3072
	v_add_u32_e32 v144, s2, v147
	ds_read_b128 v[158:161], v144
	ds_read_b128 v[162:165], v144 offset:1024
	ds_read_b128 v[166:169], v144 offset:2048
	ds_read_b128 v[170:173], v144 offset:3072
	v_lshl_add_u64 v[144:145], s[8:9], 0, v[132:133]
	s_add_i32 m0, s62, 0xc000
	ds_read_b128 v[174:177], v149
	ds_read_b128 v[178:181], v149 offset:1024
	ds_read_b128 v[182:185], v149 offset:2048
	ds_read_b128 v[186:189], v149 offset:3072
	ds_read_b128 v[190:193], v149 offset:4096
	ds_read_b128 v[210:213], v149 offset:5120
	ds_read_b128 v[222:225], v149 offset:6144
	ds_read_b128 v[228:231], v149 offset:7168
	global_load_lds_dwordx4 v[144:145], off
	v_lshl_add_u64 v[144:145], s[8:9], 0, v[134:135]
	s_add_i32 m0, s62, 0xe000
	s_nop 0
	global_load_lds_dwordx4 v[144:145], off
	s_waitcnt vmcnt(8)
	s_waitcnt lgkmcnt(0)
	s_barrier
	s_setprio 1
	s_waitcnt lgkmcnt(0)
	v_mfma_f32_16x16x32_bf16 v[126:129], v[136:139], v[174:177], v[126:129]
	v_mfma_f32_16x16x32_bf16 v[126:129], v[140:143], v[178:181], v[126:129]
	v_mfma_f32_16x16x32_bf16 v[122:125], v[150:153], v[174:177], v[122:125]
	v_mfma_f32_16x16x32_bf16 v[122:125], v[154:157], v[178:181], v[122:125]
	v_mfma_f32_16x16x32_bf16 v[110:113], v[136:139], v[182:185], v[110:113]
	v_mfma_f32_16x16x32_bf16 v[110:113], v[140:143], v[186:189], v[110:113]
	v_mfma_f32_16x16x32_bf16 v[106:109], v[150:153], v[182:185], v[106:109]
	v_mfma_f32_16x16x32_bf16 v[106:109], v[154:157], v[186:189], v[106:109]
	v_mfma_f32_16x16x32_bf16 v[94:97], v[136:139], v[190:193], v[94:97]
	v_mfma_f32_16x16x32_bf16 v[94:97], v[140:143], v[210:213], v[94:97]
	v_mfma_f32_16x16x32_bf16 v[90:93], v[150:153], v[190:193], v[90:93]
	v_mfma_f32_16x16x32_bf16 v[90:93], v[154:157], v[210:213], v[90:93]
	v_mfma_f32_16x16x32_bf16 v[78:81], v[136:139], v[222:225], v[78:81]
	v_mfma_f32_16x16x32_bf16 v[78:81], v[140:143], v[228:231], v[78:81]
	v_mfma_f32_16x16x32_bf16 v[74:77], v[150:153], v[222:225], v[74:77]
	v_mfma_f32_16x16x32_bf16 v[74:77], v[154:157], v[228:231], v[74:77]
	s_setprio 0
	s_setprio 1
	v_mfma_f32_16x16x32_bf16 v[118:121], v[158:161], v[174:177], v[118:121]
	v_mfma_f32_16x16x32_bf16 v[118:121], v[162:165], v[178:181], v[118:121]
	v_mfma_f32_16x16x32_bf16 v[114:117], v[166:169], v[174:177], v[114:117]
	v_mfma_f32_16x16x32_bf16 v[114:117], v[170:173], v[178:181], v[114:117]
	v_mfma_f32_16x16x32_bf16 v[102:105], v[158:161], v[182:185], v[102:105]
	v_mfma_f32_16x16x32_bf16 v[102:105], v[162:165], v[186:189], v[102:105]
	v_mfma_f32_16x16x32_bf16 v[98:101], v[166:169], v[182:185], v[98:101]
	v_mfma_f32_16x16x32_bf16 v[98:101], v[170:173], v[186:189], v[98:101]
	v_mfma_f32_16x16x32_bf16 v[86:89], v[158:161], v[190:193], v[86:89]
	v_mfma_f32_16x16x32_bf16 v[86:89], v[162:165], v[210:213], v[86:89]
	v_mfma_f32_16x16x32_bf16 v[82:85], v[166:169], v[190:193], v[82:85]
	v_mfma_f32_16x16x32_bf16 v[82:85], v[170:173], v[210:213], v[82:85]
	v_mfma_f32_16x16x32_bf16 v[70:73], v[158:161], v[222:225], v[70:73]
	v_mfma_f32_16x16x32_bf16 v[70:73], v[162:165], v[228:231], v[70:73]
	v_mfma_f32_16x16x32_bf16 v[66:69], v[166:169], v[222:225], v[66:69]
	v_mfma_f32_16x16x32_bf16 v[66:69], v[170:173], v[228:231], v[66:69]
	s_setprio 0
	s_barrier
	s_add_i32 s33, s33, s36
	v_lshl_add_u64 v[144:145], s[10:11], 0, v[0:1]
	s_mov_b32 m0, s33
	ds_read_b128 v[174:177], v149 offset:16384
	ds_read_b128 v[178:181], v149 offset:17408
	ds_read_b128 v[182:185], v149 offset:18432
	ds_read_b128 v[186:189], v149 offset:19456
	ds_read_b128 v[190:193], v149 offset:20480
	ds_read_b128 v[210:213], v149 offset:21504
	ds_read_b128 v[222:225], v149 offset:22528
	ds_read_b128 v[228:231], v149 offset:23552
	global_load_lds_dwordx4 v[144:145], off
	s_add_i32 m0, s33, 0x2000
	s_add_u32 s78, s10, 0x80000
	v_lshl_add_u64 v[194:195], s[10:11], 0, v[130:131]
	s_addc_u32 s79, s11, 0
	s_add_i32 s2, s2, s36
	global_load_lds_dwordx4 v[194:195], off
	v_lshl_add_u64 v[214:215], s[78:79], 0, v[0:1]
	s_mov_b32 m0, s2
	v_lshl_add_u64 v[232:233], s[58:59], 0, v[130:131]
	global_load_lds_dwordx4 v[214:215], off
	v_lshl_add_u64 v[214:215], s[78:79], 0, v[130:131]
	s_add_i32 m0, s2, 0x2000
	s_nop 0
	global_load_lds_dwordx4 v[214:215], off
	v_lshl_add_u64 v[214:215], s[58:59], 0, v[0:1]
	s_mov_b32 m0, s62
	s_nop 0
	global_load_lds_dwordx4 v[214:215], off
	s_mov_b32 m0, s63
	s_nop 0
	global_load_lds_dwordx4 v[232:233], off
	s_waitcnt vmcnt(8)
	s_waitcnt lgkmcnt(0)
	s_barrier
; #define PG8_STAGE(bufoff, gbase, voff) do { _Pragma("unroll") for (int _i = 0; _i < 2; ++_i) \
;         __builtin_amdgcn_global_load_lds((const unsigned*)((const char*)(gbase) + (voff)[_i]), (PG8_LAS unsigned*)(lds + (bufoff) + ldsw + _i * 8192), 16, 0, 0); } while (0)
; #define PG8_LDA(dst, b, h) do { _Pragma("unroll") for (int m = 0; m < 4; ++m) _Pragma("unroll") for (int k = 0; k < 2; ++k) dst[m][k] = *(const PG8_LAS bf16x8*)(lds + PG8_SA(b, h) + aoff + m * 2048 + k * 1024); } while (0)
; #define PG8_LDB(dst, b, h) do { _Pragma("unroll") for (int n = 0; n < 2; ++n) _Pragma("unroll") for (int k = 0; k < 2; ++k) dst[n][k] = *(const PG8_LAS bf16x8*)(lds + PG8_SB(b, h) + boff + n * 2048 + k * 1024); } while (0)
; #define PG8_MMA(ai, bj, At, Bt) do { __builtin_amdgcn_s_setprio(1); _Pragma("unroll") for (int m = 0; m < 4; ++m) _Pragma("unroll") for (int n = 0; n < 2; ++n) _Pragma("unroll") for (int k = 0; k < 2; ++k) \
;         acc[ai][bj][m][n] = __builtin_amdgcn_mfma_f32_16x16x32_bf16(Bt[n][k], At[m][k], acc[ai][bj][m][n], 0, 0, 0); __builtin_amdgcn_s_setprio(0); } while (0)
; #define PG8_WAIT_V(n) asm volatile("s_waitcnt vmcnt(" #n ")" ::: "memory")
; #define PG8_WAIT_L(n) asm volatile("s_waitcnt lgkmcnt(" #n ")" ::: "memory")
; #define PG8_BAR __builtin_amdgcn_s_barrier()
; #define PG8_SCHED __builtin_amdgcn_sched_barrier(0)
; template <class Epi, class Sched, bool ALIGN_EPI = false, bool SP2 = false>
; __device__ __forceinline__ void gemm_phase(PG8_LAS unsigned char* lds, const Gemm g, const Sched& S, const Epi& E) {
;     ...
;             PG8_WAIT_V(8); PG8_WAIT_L(0); PG8_BAR; PG8_MMA(1, 0, At, B0); PG8_MMA(1, 1, At, B1); PG8_BAR; PG8_SCHED;
;             PG8_LDB(B0, 1, 0); PG8_LDB(B1, 1, 1); PG8_SCHED; PG8_LDA(At, 1, 0); PG8_STAGE(PG8_SA(0, 1), a2 + hstepA, voffA);
;             PG8_WAIT_V(8); PG8_WAIT_L(0); PG8_BAR; PG8_MMA(0, 0, At, B0); PG8_MMA(0, 1, At, B1); PG8_BAR; PG8_SCHED;
	s_setprio 1
	s_waitcnt lgkmcnt(0)
	v_mfma_f32_16x16x32_bf16 v[62:65], v[136:139], v[174:177], v[62:65]
	v_mfma_f32_16x16x32_bf16 v[62:65], v[140:143], v[178:181], v[62:65]
	v_mfma_f32_16x16x32_bf16 v[58:61], v[150:153], v[174:177], v[58:61]
	v_mfma_f32_16x16x32_bf16 v[58:61], v[154:157], v[178:181], v[58:61]
	v_mfma_f32_16x16x32_bf16 v[46:49], v[136:139], v[182:185], v[46:49]
	v_mfma_f32_16x16x32_bf16 v[46:49], v[140:143], v[186:189], v[46:49]
	v_mfma_f32_16x16x32_bf16 v[42:45], v[150:153], v[182:185], v[42:45]
	v_mfma_f32_16x16x32_bf16 v[42:45], v[154:157], v[186:189], v[42:45]
	v_mfma_f32_16x16x32_bf16 v[30:33], v[136:139], v[190:193], v[30:33]
	v_mfma_f32_16x16x32_bf16 v[30:33], v[140:143], v[210:213], v[30:33]
	v_mfma_f32_16x16x32_bf16 v[26:29], v[150:153], v[190:193], v[26:29]
	v_mfma_f32_16x16x32_bf16 v[26:29], v[154:157], v[210:213], v[26:29]
	v_mfma_f32_16x16x32_bf16 v[14:17], v[136:139], v[222:225], v[14:17]
	v_mfma_f32_16x16x32_bf16 v[14:17], v[140:143], v[228:231], v[14:17]
	v_mfma_f32_16x16x32_bf16 v[10:13], v[150:153], v[222:225], v[10:13]
	v_mfma_f32_16x16x32_bf16 v[10:13], v[154:157], v[228:231], v[10:13]
	s_setprio 0
	s_setprio 1
	v_mfma_f32_16x16x32_bf16 v[54:57], v[158:161], v[174:177], v[54:57]
	v_mfma_f32_16x16x32_bf16 v[54:57], v[162:165], v[178:181], v[54:57]
	v_mfma_f32_16x16x32_bf16 v[50:53], v[166:169], v[174:177], v[50:53]
	v_mfma_f32_16x16x32_bf16 v[50:53], v[170:173], v[178:181], v[50:53]
	v_mfma_f32_16x16x32_bf16 v[38:41], v[158:161], v[182:185], v[38:41]
	v_mfma_f32_16x16x32_bf16 v[38:41], v[162:165], v[186:189], v[38:41]
	v_mfma_f32_16x16x32_bf16 v[34:37], v[166:169], v[182:185], v[34:37]
	v_mfma_f32_16x16x32_bf16 v[34:37], v[170:173], v[186:189], v[34:37]
	v_mfma_f32_16x16x32_bf16 v[22:25], v[158:161], v[190:193], v[22:25]
	v_mfma_f32_16x16x32_bf16 v[22:25], v[162:165], v[210:213], v[22:25]
	v_mfma_f32_16x16x32_bf16 v[18:21], v[166:169], v[190:193], v[18:21]
	v_mfma_f32_16x16x32_bf16 v[18:21], v[170:173], v[210:213], v[18:21]
	v_mfma_f32_16x16x32_bf16 v[6:9], v[158:161], v[222:225], v[6:9]
	v_mfma_f32_16x16x32_bf16 v[6:9], v[162:165], v[228:231], v[6:9]
	v_mfma_f32_16x16x32_bf16 v[2:5], v[166:169], v[222:225], v[2:5]
	v_mfma_f32_16x16x32_bf16 v[2:5], v[170:173], v[228:231], v[2:5]
	s_setprio 0
	s_barrier
	s_add_i32 s2, s87, 0x100
	s_add_i32 s33, s69, 0x100
	v_add_u32_e32 v154, s2, v147
	v_add_u32_e32 v170, s33, v147
	ds_read_b128 v[136:139], v154
	ds_read_b128 v[140:143], v154 offset:1024
	ds_read_b128 v[150:153], v154 offset:2048
	ds_read_b128 v[154:157], v154 offset:3072
	ds_read_b128 v[158:161], v170
	ds_read_b128 v[162:165], v170 offset:1024
	ds_read_b128 v[166:169], v170 offset:2048
	ds_read_b128 v[170:173], v170 offset:3072
	s_add_u32 s58, s58, 0x80000
	s_addc_u32 s59, s59, 0
	s_mov_b32 m0, s65
	v_lshl_add_u64 v[234:235], s[58:59], 0, v[0:1]
	ds_read_b128 v[174:177], v149 offset:32768
	ds_read_b128 v[178:181], v149 offset:33792
	ds_read_b128 v[182:185], v149 offset:34816
	ds_read_b128 v[186:189], v149 offset:35840
	ds_read_b128 v[190:193], v149 offset:36864
	ds_read_b128 v[210:213], v149 offset:37888
	ds_read_b128 v[222:225], v149 offset:38912
	ds_read_b128 v[228:231], v149 offset:39936
	global_load_lds_dwordx4 v[234:235], off
	v_lshl_add_u64 v[234:235], s[58:59], 0, v[130:131]
	s_mov_b32 m0, s72
	s_nop 0
	global_load_lds_dwordx4 v[234:235], off
	s_waitcnt vmcnt(8)
	s_waitcnt lgkmcnt(0)
	s_barrier
	s_setprio 1
	s_waitcnt lgkmcnt(0)
	v_mfma_f32_16x16x32_bf16 v[126:129], v[136:139], v[174:177], v[126:129]
	v_mfma_f32_16x16x32_bf16 v[126:129], v[140:143], v[178:181], v[126:129]
	v_mfma_f32_16x16x32_bf16 v[122:125], v[150:153], v[174:177], v[122:125]
	v_mfma_f32_16x16x32_bf16 v[122:125], v[154:157], v[178:181], v[122:125]
	v_mfma_f32_16x16x32_bf16 v[110:113], v[136:139], v[182:185], v[110:113]
	v_mfma_f32_16x16x32_bf16 v[110:113], v[140:143], v[186:189], v[110:113]
	v_mfma_f32_16x16x32_bf16 v[106:109], v[150:153], v[182:185], v[106:109]
	v_mfma_f32_16x16x32_bf16 v[106:109], v[154:157], v[186:189], v[106:109]
	v_mfma_f32_16x16x32_bf16 v[94:97], v[136:139], v[190:193], v[94:97]
	v_mfma_f32_16x16x32_bf16 v[94:97], v[140:143], v[210:213], v[94:97]
	v_mfma_f32_16x16x32_bf16 v[90:93], v[150:153], v[190:193], v[90:93]
	v_mfma_f32_16x16x32_bf16 v[90:93], v[154:157], v[210:213], v[90:93]
	v_mfma_f32_16x16x32_bf16 v[78:81], v[136:139], v[222:225], v[78:81]
	v_mfma_f32_16x16x32_bf16 v[78:81], v[140:143], v[228:231], v[78:81]
	v_mfma_f32_16x16x32_bf16 v[74:77], v[150:153], v[222:225], v[74:77]
	v_mfma_f32_16x16x32_bf16 v[74:77], v[154:157], v[228:231], v[74:77]
	s_setprio 0
	s_setprio 1
	v_mfma_f32_16x16x32_bf16 v[118:121], v[158:161], v[174:177], v[118:121]
	v_mfma_f32_16x16x32_bf16 v[118:121], v[162:165], v[178:181], v[118:121]
	v_mfma_f32_16x16x32_bf16 v[114:117], v[166:169], v[174:177], v[114:117]
	v_mfma_f32_16x16x32_bf16 v[114:117], v[170:173], v[178:181], v[114:117]
	v_mfma_f32_16x16x32_bf16 v[102:105], v[158:161], v[182:185], v[102:105]
	v_mfma_f32_16x16x32_bf16 v[102:105], v[162:165], v[186:189], v[102:105]
	v_mfma_f32_16x16x32_bf16 v[98:101], v[166:169], v[182:185], v[98:101]
	v_mfma_f32_16x16x32_bf16 v[98:101], v[170:173], v[186:189], v[98:101]
	v_mfma_f32_16x16x32_bf16 v[86:89], v[158:161], v[190:193], v[86:89]
	v_mfma_f32_16x16x32_bf16 v[86:89], v[162:165], v[210:213], v[86:89]
	v_mfma_f32_16x16x32_bf16 v[82:85], v[166:169], v[190:193], v[82:85]
	v_mfma_f32_16x16x32_bf16 v[82:85], v[170:173], v[210:213], v[82:85]
	v_mfma_f32_16x16x32_bf16 v[70:73], v[158:161], v[222:225], v[70:73]
	v_mfma_f32_16x16x32_bf16 v[70:73], v[162:165], v[228:231], v[70:73]
	v_mfma_f32_16x16x32_bf16 v[66:69], v[166:169], v[222:225], v[66:69]
	v_mfma_f32_16x16x32_bf16 v[66:69], v[170:173], v[228:231], v[66:69]
	s_setprio 0
	s_barrier
; #define PG8_STAGE(bufoff, gbase, voff) do { _Pragma("unroll") for (int _i = 0; _i < 2; ++_i) \
;         __builtin_amdgcn_global_load_lds((const unsigned*)((const char*)(gbase) + (voff)[_i]), (PG8_LAS unsigned*)(lds + (bufoff) + ldsw + _i * 8192), 16, 0, 0); } while (0)
; #define PG8_LDA(dst, b, h) do { _Pragma("unroll") for (int m = 0; m < 4; ++m) _Pragma("unroll") for (int k = 0; k < 2; ++k) dst[m][k] = *(const PG8_LAS bf16x8*)(lds + PG8_SA(b, h) + aoff + m * 2048 + k * 1024); } while (0)
; #define PG8_MMA(ai, bj, At, Bt) do { __builtin_amdgcn_s_setprio(1); _Pragma("unroll") for (int m = 0; m < 4; ++m) _Pragma("unroll") for (int n = 0; n < 2; ++n) _Pragma("unroll") for (int k = 0; k < 2; ++k) \
;         acc[ai][bj][m][n] = __builtin_amdgcn_mfma_f32_16x16x32_bf16(Bt[n][k], At[m][k], acc[ai][bj][m][n], 0, 0, 0); __builtin_amdgcn_s_setprio(0); } while (0)
; #define PG8_WAIT_V(n) asm volatile("s_waitcnt vmcnt(" #n ")" ::: "memory")
; #define PG8_WAIT_L(n) asm volatile("s_waitcnt lgkmcnt(" #n ")" ::: "memory")
; #define PG8_BAR __builtin_amdgcn_s_barrier()
; #define PG8_SCHED __builtin_amdgcn_sched_barrier(0)
; template <class Epi, class Sched, bool ALIGN_EPI = false, bool SP2 = false>
; __device__ __forceinline__ void gemm_phase(PG8_LAS unsigned char* lds, const Gemm g, const Sched& S, const Epi& E) {
;     ...
;             PG8_LDA(At, 1, 1); PG8_STAGE(PG8_SB(1, 0), b3, voffB); PG8_STAGE(PG8_SB(1, 1), b3 + hstepB, voffB); PG8_STAGE(PG8_SA(1, 0), a3, voffA);
;             PG8_WAIT_V(8); PG8_WAIT_L(0); PG8_BAR; PG8_MMA(1, 0, At, B0); PG8_MMA(1, 1, At, B1); PG8_BAR; PG8_SCHED;
	s_add_i32 s2, s2, s36
	v_lshl_add_u64 v[144:145], v[144:145], 0, s[94:95]
	s_mov_b32 m0, s2
	ds_read_b128 v[174:177], v149 offset:49152
	ds_read_b128 v[178:181], v149 offset:50176
	ds_read_b128 v[182:185], v149 offset:51200
	ds_read_b128 v[186:189], v149 offset:52224
	ds_read_b128 v[190:193], v149 offset:53248
	ds_read_b128 v[210:213], v149 offset:54272
	ds_read_b128 v[222:225], v149 offset:55296
	ds_read_b128 v[228:231], v149 offset:56320
	global_load_lds_dwordx4 v[144:145], off
	s_add_i32 m0, s2, 0x2000
	s_add_u32 s10, s10, 0x80080
	v_lshl_add_u64 v[144:145], v[194:195], 0, s[94:95]
	s_addc_u32 s11, s11, 0
	s_add_i32 s2, s33, s36
	global_load_lds_dwordx4 v[144:145], off
	v_lshl_add_u64 v[144:145], s[10:11], 0, v[0:1]
	s_mov_b32 m0, s2
	s_nop 0
	global_load_lds_dwordx4 v[144:145], off
	v_lshl_add_u64 v[144:145], s[10:11], 0, v[130:131]
	s_add_i32 m0, s2, 0x2000
	s_nop 0
	global_load_lds_dwordx4 v[144:145], off
	v_lshl_add_u64 v[144:145], v[214:215], 0, s[94:95]
	s_mov_b32 m0, s73
	s_nop 0
	global_load_lds_dwordx4 v[144:145], off
	v_lshl_add_u64 v[144:145], v[232:233], 0, s[94:95]
	s_mov_b32 m0, s76
	s_nop 0
	global_load_lds_dwordx4 v[144:145], off
	s_waitcnt vmcnt(8)
	s_waitcnt lgkmcnt(0)
	s_barrier
	s_setprio 1
	s_waitcnt lgkmcnt(0)
	v_mfma_f32_16x16x32_bf16 v[62:65], v[136:139], v[174:177], v[62:65]
	v_mfma_f32_16x16x32_bf16 v[62:65], v[140:143], v[178:181], v[62:65]
	v_mfma_f32_16x16x32_bf16 v[58:61], v[150:153], v[174:177], v[58:61]
	v_mfma_f32_16x16x32_bf16 v[58:61], v[154:157], v[178:181], v[58:61]
	v_mfma_f32_16x16x32_bf16 v[46:49], v[136:139], v[182:185], v[46:49]
	v_mfma_f32_16x16x32_bf16 v[46:49], v[140:143], v[186:189], v[46:49]
	v_mfma_f32_16x16x32_bf16 v[42:45], v[150:153], v[182:185], v[42:45]
	v_mfma_f32_16x16x32_bf16 v[42:45], v[154:157], v[186:189], v[42:45]
	v_mfma_f32_16x16x32_bf16 v[30:33], v[136:139], v[190:193], v[30:33]
	v_mfma_f32_16x16x32_bf16 v[30:33], v[140:143], v[210:213], v[30:33]
	v_mfma_f32_16x16x32_bf16 v[26:29], v[150:153], v[190:193], v[26:29]
	v_mfma_f32_16x16x32_bf16 v[26:29], v[154:157], v[210:213], v[26:29]
	v_mfma_f32_16x16x32_bf16 v[14:17], v[136:139], v[222:225], v[14:17]
	v_mfma_f32_16x16x32_bf16 v[14:17], v[140:143], v[228:231], v[14:17]
	v_mfma_f32_16x16x32_bf16 v[10:13], v[150:153], v[222:225], v[10:13]
	v_mfma_f32_16x16x32_bf16 v[10:13], v[154:157], v[228:231], v[10:13]
	s_setprio 0
	s_setprio 1
	v_mfma_f32_16x16x32_bf16 v[54:57], v[158:161], v[174:177], v[54:57]
	v_mfma_f32_16x16x32_bf16 v[54:57], v[162:165], v[178:181], v[54:57]
	v_mfma_f32_16x16x32_bf16 v[50:53], v[166:169], v[174:177], v[50:53]
	v_mfma_f32_16x16x32_bf16 v[50:53], v[170:173], v[178:181], v[50:53]
	v_mfma_f32_16x16x32_bf16 v[38:41], v[158:161], v[182:185], v[38:41]
	v_mfma_f32_16x16x32_bf16 v[38:41], v[162:165], v[186:189], v[38:41]
	v_mfma_f32_16x16x32_bf16 v[34:37], v[166:169], v[182:185], v[34:37]
	v_mfma_f32_16x16x32_bf16 v[34:37], v[170:173], v[186:189], v[34:37]
	v_mfma_f32_16x16x32_bf16 v[22:25], v[158:161], v[190:193], v[22:25]
	v_mfma_f32_16x16x32_bf16 v[22:25], v[162:165], v[210:213], v[22:25]
	v_mfma_f32_16x16x32_bf16 v[18:21], v[166:169], v[190:193], v[18:21]
	v_mfma_f32_16x16x32_bf16 v[18:21], v[170:173], v[210:213], v[18:21]
	v_mfma_f32_16x16x32_bf16 v[6:9], v[158:161], v[222:225], v[6:9]
	v_mfma_f32_16x16x32_bf16 v[6:9], v[162:165], v[228:231], v[6:9]
	v_mfma_f32_16x16x32_bf16 v[2:5], v[166:169], v[222:225], v[2:5]
	v_mfma_f32_16x16x32_bf16 v[2:5], v[170:173], v[228:231], v[2:5]
	s_setprio 0
	s_barrier
	s_add_i32 s91, s91, 2
	s_add_u32 s8, s8, 0x100
	s_addc_u32 s9, s9, 0
	s_add_u32 s74, s74, 0x100
	s_addc_u32 s83, s83, 0
	s_cmp_gt_u32 s91, 29
	s_cbranch_scc0 .LBB0_456
	s_and_b64 vcc, exec, s[38:39]
	s_cbranch_vccz .LBB0_459
	s_barrier

; #define PG8_STAGE(bufoff, gbase, voff) do { _Pragma("unroll") for (int _i = 0; _i < 2; ++_i) \
;         __builtin_amdgcn_global_load_lds((const unsigned*)((const char*)(gbase) + (voff)[_i]), (PG8_LAS unsigned*)(lds + (bufoff) + ldsw + _i * 8192), 16, 0, 0); } while (0)
; #define PG8_LDA(dst, b, h) do { _Pragma("unroll") for (int m = 0; m < 4; ++m) _Pragma("unroll") for (int k = 0; k < 2; ++k) dst[m][k] = *(const PG8_LAS bf16x8*)(lds + PG8_SA(b, h) + aoff + m * 2048 + k * 1024); } while (0)
; #define PG8_LDB(dst, b, h) do { _Pragma("unroll") for (int n = 0; n < 2; ++n) _Pragma("unroll") for (int k = 0; k < 2; ++k) dst[n][k] = *(const PG8_LAS bf16x8*)(lds + PG8_SB(b, h) + boff + n * 2048 + k * 1024); } while (0)
; #define PG8_MMA(ai, bj, At, Bt) do { __builtin_amdgcn_s_setprio(1); _Pragma("unroll") for (int m = 0; m < 4; ++m) _Pragma("unroll") for (int n = 0; n < 2; ++n) _Pragma("unroll") for (int k = 0; k < 2; ++k) \
;         acc[ai][bj][m][n] = __builtin_amdgcn_mfma_f32_16x16x32_bf16(Bt[n][k], At[m][k], acc[ai][bj][m][n], 0, 0, 0); __builtin_amdgcn_s_setprio(0); } while (0)
; #define PG8_WAIT_V(n) asm volatile("s_waitcnt vmcnt(" #n ")" ::: "memory")
; #define PG8_WAIT_L(n) asm volatile("s_waitcnt lgkmcnt(" #n ")" ::: "memory")
; #define PG8_BAR __builtin_amdgcn_s_barrier()
; #define PG8_SCHED __builtin_amdgcn_sched_barrier(0)
; template <class Epi, class Sched, bool ALIGN_EPI = false, bool SP2 = false>
; __device__ __forceinline__ void gemm_phase(PG8_LAS unsigned char* lds, const Gemm g, const Sched& S, const Epi& E) {
;     ...
;             const bool last = (t == nt - 2);
;             const char* a1 = cA + (size_t)(t + 1) * kstep;
;             const char* a2 = last ? nA : cA + (size_t)(t + 2) * kstep; const char* b2 = last ? nB : cB + (size_t)(t + 2) * kstep;
;             const char* a3 = a2 + kstep; const char* b3 = b2 + kstep;
;             if (last && has_next) S.a_ready(nxt);
;             if constexpr (SP2) {
;             PG8_LDB(B0, 0, 0); PG8_LDB(B1, 0, 1); PG8_SCHED; PG8_LDA(At, 0, 0); PG8_STAGE(PG8_SA(1, 1), a1 + hstepA, voffA);
;             PG8_WAIT_V(8); PG8_WAIT_L(0); PG8_BAR; PG8_MMA(0, 0, At, B0); PG8_MMA(0, 1, At, B1); PG8_BAR; PG8_SCHED;
;             PG8_LDA(At, 0, 1); PG8_STAGE(PG8_SB(0, 0), b2, voffB); PG8_STAGE(PG8_SB(0, 1), b2 + hstepB, voffB); PG8_STAGE(PG8_SA(0, 0), a2, voffA);
.LBB0_1434:
	s_add_u32 s2, s6, 0xfff80080
	s_addc_u32 s33, s7, -1
	s_add_i32 s63, s17, 0x100
	s_cmp_eq_u32 s62, 28
	s_cselect_b32 s45, s35, s33
	s_cselect_b32 s44, s58, s2
	v_add_u32_e32 v146, s63, v149
	s_cselect_b32 s43, s27, s61
	s_cselect_b32 s42, s59, s60
	s_add_i32 s2, s24, 0x100
	ds_read_b128 v[142:145], v146
	ds_read_b128 v[154:157], v146 offset:1024
	ds_read_b128 v[158:161], v146 offset:2048
	ds_read_b128 v[162:165], v146 offset:3072
	v_add_u32_e32 v146, s2, v149
	ds_read_b128 v[166:169], v146
	ds_read_b128 v[170:173], v146 offset:1024
	ds_read_b128 v[174:177], v146 offset:2048
	ds_read_b128 v[178:181], v146 offset:3072
	v_lshl_add_u64 v[146:147], s[6:7], 0, v[138:139]
	s_add_i32 m0, s46, 0xc000
	ds_read_b128 v[182:185], v152
	ds_read_b128 v[186:189], v152 offset:1024
	ds_read_b128 v[190:193], v152 offset:2048
	ds_read_b128 v[210:213], v152 offset:3072
	ds_read_b128 v[228:231], v152 offset:4096
	ds_read_b128 v[232:235], v152 offset:5120
	ds_read_b128 v[236:239], v152 offset:6144
	ds_read_b128 v[240:243], v152 offset:7168
	global_load_lds_dwordx4 v[146:147], off
	v_lshl_add_u64 v[146:147], s[6:7], 0, v[140:141]
	s_add_i32 m0, s46, 0xe000
	s_nop 0
	global_load_lds_dwordx4 v[146:147], off
	s_waitcnt vmcnt(8)
	s_waitcnt lgkmcnt(0)
	s_barrier
	s_setprio 1
	s_waitcnt lgkmcnt(0)
	v_mfma_f32_16x16x32_bf16 v[126:129], v[142:145], v[182:185], v[126:129]
	v_mfma_f32_16x16x32_bf16 v[126:129], v[154:157], v[186:189], v[126:129]
	v_mfma_f32_16x16x32_bf16 v[122:125], v[158:161], v[182:185], v[122:125]
	v_mfma_f32_16x16x32_bf16 v[122:125], v[162:165], v[186:189], v[122:125]
	v_mfma_f32_16x16x32_bf16 v[110:113], v[142:145], v[190:193], v[110:113]
	v_mfma_f32_16x16x32_bf16 v[110:113], v[154:157], v[210:213], v[110:113]
	v_mfma_f32_16x16x32_bf16 v[106:109], v[158:161], v[190:193], v[106:109]
	v_mfma_f32_16x16x32_bf16 v[106:109], v[162:165], v[210:213], v[106:109]
	v_mfma_f32_16x16x32_bf16 v[94:97], v[142:145], v[228:231], v[94:97]
	v_mfma_f32_16x16x32_bf16 v[94:97], v[154:157], v[232:235], v[94:97]
	v_mfma_f32_16x16x32_bf16 v[90:93], v[158:161], v[228:231], v[90:93]
	v_mfma_f32_16x16x32_bf16 v[90:93], v[162:165], v[232:235], v[90:93]
	v_mfma_f32_16x16x32_bf16 v[78:81], v[142:145], v[236:239], v[78:81]
	v_mfma_f32_16x16x32_bf16 v[78:81], v[154:157], v[240:243], v[78:81]
	v_mfma_f32_16x16x32_bf16 v[74:77], v[158:161], v[236:239], v[74:77]
	v_mfma_f32_16x16x32_bf16 v[74:77], v[162:165], v[240:243], v[74:77]
	s_setprio 0
	s_cmp_eq_u32 s53, 18
	s_cbranch_scc1 .Linp_skip_0
	s_setprio 1
	v_mfma_f32_16x16x32_bf16 v[118:121], v[166:169], v[182:185], v[118:121]
	v_mfma_f32_16x16x32_bf16 v[118:121], v[170:173], v[186:189], v[118:121]
	v_mfma_f32_16x16x32_bf16 v[114:117], v[174:177], v[182:185], v[114:117]
	v_mfma_f32_16x16x32_bf16 v[114:117], v[178:181], v[186:189], v[114:117]
	v_mfma_f32_16x16x32_bf16 v[102:105], v[166:169], v[190:193], v[102:105]
	v_mfma_f32_16x16x32_bf16 v[102:105], v[170:173], v[210:213], v[102:105]
	v_mfma_f32_16x16x32_bf16 v[98:101], v[174:177], v[190:193], v[98:101]
	v_mfma_f32_16x16x32_bf16 v[98:101], v[178:181], v[210:213], v[98:101]
	v_mfma_f32_16x16x32_bf16 v[86:89], v[166:169], v[228:231], v[86:89]
	v_mfma_f32_16x16x32_bf16 v[86:89], v[170:173], v[232:235], v[86:89]
	v_mfma_f32_16x16x32_bf16 v[82:85], v[174:177], v[228:231], v[82:85]
	v_mfma_f32_16x16x32_bf16 v[82:85], v[178:181], v[232:235], v[82:85]
	v_mfma_f32_16x16x32_bf16 v[70:73], v[166:169], v[236:239], v[70:73]
	v_mfma_f32_16x16x32_bf16 v[70:73], v[170:173], v[240:243], v[70:73]
	v_mfma_f32_16x16x32_bf16 v[66:69], v[174:177], v[236:239], v[66:69]
	v_mfma_f32_16x16x32_bf16 v[66:69], v[178:181], v[240:243], v[66:69]
	s_setprio 0
.Linp_skip_0:
	s_barrier
	s_add_i32 s33, s63, s36
	v_lshl_add_u64 v[146:147], s[42:43], 0, v[0:1]
	s_mov_b32 m0, s33
	ds_read_b128 v[182:185], v152 offset:16384
	ds_read_b128 v[186:189], v152 offset:17408
	ds_read_b128 v[190:193], v152 offset:18432
	ds_read_b128 v[210:213], v152 offset:19456
	ds_read_b128 v[228:231], v152 offset:20480
	ds_read_b128 v[232:235], v152 offset:21504
	ds_read_b128 v[236:239], v152 offset:22528
	ds_read_b128 v[240:243], v152 offset:23552
	global_load_lds_dwordx4 v[146:147], off
	s_add_i32 m0, s33, 0x2000
	s_add_u32 s72, s42, 0x80000
	v_lshl_add_u64 v[194:195], s[42:43], 0, v[132:133]
	s_addc_u32 s73, s43, 0
	s_add_i32 s2, s2, s36
	global_load_lds_dwordx4 v[194:195], off
	v_lshl_add_u64 v[214:215], s[72:73], 0, v[0:1]
	s_mov_b32 m0, s2
	v_lshl_add_u64 v[222:223], s[44:45], 0, v[134:135]
	global_load_lds_dwordx4 v[214:215], off
	v_lshl_add_u64 v[214:215], s[72:73], 0, v[132:133]
	s_add_i32 m0, s2, 0x2000
	s_nop 0
	global_load_lds_dwordx4 v[214:215], off
	v_lshl_add_u64 v[214:215], s[44:45], 0, v[136:137]
	s_mov_b32 m0, s46
	s_nop 0
	global_load_lds_dwordx4 v[214:215], off
	s_mov_b32 m0, s47
	s_nop 0
	global_load_lds_dwordx4 v[222:223], off
	s_waitcnt vmcnt(8)
	s_waitcnt lgkmcnt(0)
	s_barrier
	s_setprio 1
	s_waitcnt lgkmcnt(0)
	v_mfma_f32_16x16x32_bf16 v[62:65], v[142:145], v[182:185], v[62:65]
	v_mfma_f32_16x16x32_bf16 v[62:65], v[154:157], v[186:189], v[62:65]
	v_mfma_f32_16x16x32_bf16 v[58:61], v[158:161], v[182:185], v[58:61]
	v_mfma_f32_16x16x32_bf16 v[58:61], v[162:165], v[186:189], v[58:61]
	v_mfma_f32_16x16x32_bf16 v[46:49], v[142:145], v[190:193], v[46:49]
	v_mfma_f32_16x16x32_bf16 v[46:49], v[154:157], v[210:213], v[46:49]
	v_mfma_f32_16x16x32_bf16 v[42:45], v[158:161], v[190:193], v[42:45]
	v_mfma_f32_16x16x32_bf16 v[42:45], v[162:165], v[210:213], v[42:45]
	v_mfma_f32_16x16x32_bf16 v[30:33], v[142:145], v[228:231], v[30:33]
	v_mfma_f32_16x16x32_bf16 v[30:33], v[154:157], v[232:235], v[30:33]
	v_mfma_f32_16x16x32_bf16 v[26:29], v[158:161], v[228:231], v[26:29]
	v_mfma_f32_16x16x32_bf16 v[26:29], v[162:165], v[232:235], v[26:29]
	v_mfma_f32_16x16x32_bf16 v[14:17], v[142:145], v[236:239], v[14:17]
	v_mfma_f32_16x16x32_bf16 v[14:17], v[154:157], v[240:243], v[14:17]
	v_mfma_f32_16x16x32_bf16 v[10:13], v[158:161], v[236:239], v[10:13]
	v_mfma_f32_16x16x32_bf16 v[10:13], v[162:165], v[240:243], v[10:13]
	s_setprio 0
	s_cmp_eq_u32 s53, 18
	s_cbranch_scc1 .Linp_skip_1
; #define PG8_STAGE(bufoff, gbase, voff) do { _Pragma("unroll") for (int _i = 0; _i < 2; ++_i) \
;         __builtin_amdgcn_global_load_lds((const unsigned*)((const char*)(gbase) + (voff)[_i]), (PG8_LAS unsigned*)(lds + (bufoff) + ldsw + _i * 8192), 16, 0, 0); } while (0)
; #define PG8_LDA(dst, b, h) do { _Pragma("unroll") for (int m = 0; m < 4; ++m) _Pragma("unroll") for (int k = 0; k < 2; ++k) dst[m][k] = *(const PG8_LAS bf16x8*)(lds + PG8_SA(b, h) + aoff + m * 2048 + k * 1024); } while (0)
; #define PG8_LDB(dst, b, h) do { _Pragma("unroll") for (int n = 0; n < 2; ++n) _Pragma("unroll") for (int k = 0; k < 2; ++k) dst[n][k] = *(const PG8_LAS bf16x8*)(lds + PG8_SB(b, h) + boff + n * 2048 + k * 1024); } while (0)
; #define PG8_MMA(ai, bj, At, Bt) do { __builtin_amdgcn_s_setprio(1); _Pragma("unroll") for (int m = 0; m < 4; ++m) _Pragma("unroll") for (int n = 0; n < 2; ++n) _Pragma("unroll") for (int k = 0; k < 2; ++k) \
;         acc[ai][bj][m][n] = __builtin_amdgcn_mfma_f32_16x16x32_bf16(Bt[n][k], At[m][k], acc[ai][bj][m][n], 0, 0, 0); __builtin_amdgcn_s_setprio(0); } while (0)
; #define PG8_WAIT_V(n) asm volatile("s_waitcnt vmcnt(" #n ")" ::: "memory")
; #define PG8_WAIT_L(n) asm volatile("s_waitcnt lgkmcnt(" #n ")" ::: "memory")
; #define PG8_BAR __builtin_amdgcn_s_barrier()
; #define PG8_SCHED __builtin_amdgcn_sched_barrier(0)
; template <class Epi, class Sched, bool ALIGN_EPI = false, bool SP2 = false>
; __device__ __forceinline__ void gemm_phase(PG8_LAS unsigned char* lds, const Gemm g, const Sched& S, const Epi& E) {
;     ...
;             PG8_WAIT_V(8); PG8_WAIT_L(0); PG8_BAR; PG8_MMA(1, 0, At, B0); PG8_MMA(1, 1, At, B1); PG8_BAR; PG8_SCHED;
;             PG8_LDB(B0, 1, 0); PG8_LDB(B1, 1, 1); PG8_SCHED; PG8_LDA(At, 1, 0); PG8_STAGE(PG8_SA(0, 1), a2 + hstepA, voffA);
;             PG8_WAIT_V(8); PG8_WAIT_L(0); PG8_BAR; PG8_MMA(0, 0, At, B0); PG8_MMA(0, 1, At, B1); PG8_BAR; PG8_SCHED;
	s_setprio 1
	v_mfma_f32_16x16x32_bf16 v[54:57], v[166:169], v[182:185], v[54:57]
	v_mfma_f32_16x16x32_bf16 v[54:57], v[170:173], v[186:189], v[54:57]
	v_mfma_f32_16x16x32_bf16 v[50:53], v[174:177], v[182:185], v[50:53]
	v_mfma_f32_16x16x32_bf16 v[50:53], v[178:181], v[186:189], v[50:53]
	v_mfma_f32_16x16x32_bf16 v[38:41], v[166:169], v[190:193], v[38:41]
	v_mfma_f32_16x16x32_bf16 v[38:41], v[170:173], v[210:213], v[38:41]
	v_mfma_f32_16x16x32_bf16 v[34:37], v[174:177], v[190:193], v[34:37]
	v_mfma_f32_16x16x32_bf16 v[34:37], v[178:181], v[210:213], v[34:37]
	v_mfma_f32_16x16x32_bf16 v[22:25], v[166:169], v[228:231], v[22:25]
	v_mfma_f32_16x16x32_bf16 v[22:25], v[170:173], v[232:235], v[22:25]
	v_mfma_f32_16x16x32_bf16 v[18:21], v[174:177], v[228:231], v[18:21]
	v_mfma_f32_16x16x32_bf16 v[18:21], v[178:181], v[232:235], v[18:21]
	v_mfma_f32_16x16x32_bf16 v[6:9], v[166:169], v[236:239], v[6:9]
	v_mfma_f32_16x16x32_bf16 v[6:9], v[170:173], v[240:243], v[6:9]
	v_mfma_f32_16x16x32_bf16 v[2:5], v[174:177], v[236:239], v[2:5]
	v_mfma_f32_16x16x32_bf16 v[2:5], v[178:181], v[240:243], v[2:5]
	s_setprio 0
.Linp_skip_1:
	s_barrier
	s_add_i32 s2, s87, 0x100
	v_add_u32_e32 v148, s2, v149
	s_add_i32 s33, s69, 0x100
	ds_read_b128 v[142:145], v148
	ds_read_b128 v[154:157], v148 offset:1024
	ds_read_b128 v[158:161], v148 offset:2048
	ds_read_b128 v[162:165], v148 offset:3072
	v_add_u32_e32 v148, s33, v149
	ds_read_b128 v[166:169], v148
	ds_read_b128 v[170:173], v148 offset:1024
	ds_read_b128 v[174:177], v148 offset:2048
	ds_read_b128 v[178:181], v148 offset:3072
	s_add_u32 s44, s44, 0x80000
	s_addc_u32 s45, s45, 0
	s_mov_b32 m0, s48
	v_lshl_add_u64 v[224:225], s[44:45], 0, v[136:137]
	ds_read_b128 v[182:185], v152 offset:32768
	ds_read_b128 v[186:189], v152 offset:33792
	ds_read_b128 v[190:193], v152 offset:34816
	ds_read_b128 v[210:213], v152 offset:35840
	ds_read_b128 v[228:231], v152 offset:36864
	ds_read_b128 v[232:235], v152 offset:37888
	ds_read_b128 v[236:239], v152 offset:38912
	ds_read_b128 v[240:243], v152 offset:39936
	global_load_lds_dwordx4 v[224:225], off
	v_lshl_add_u64 v[224:225], s[44:45], 0, v[134:135]
	s_mov_b32 m0, s49
	s_nop 0
	global_load_lds_dwordx4 v[224:225], off
	s_waitcnt vmcnt(8)
	s_waitcnt lgkmcnt(0)
	s_barrier
	s_setprio 1
	s_waitcnt lgkmcnt(0)
	v_mfma_f32_16x16x32_bf16 v[126:129], v[142:145], v[182:185], v[126:129]
	v_mfma_f32_16x16x32_bf16 v[126:129], v[154:157], v[186:189], v[126:129]
	v_mfma_f32_16x16x32_bf16 v[122:125], v[158:161], v[182:185], v[122:125]
	v_mfma_f32_16x16x32_bf16 v[122:125], v[162:165], v[186:189], v[122:125]
	v_mfma_f32_16x16x32_bf16 v[110:113], v[142:145], v[190:193], v[110:113]
	v_mfma_f32_16x16x32_bf16 v[110:113], v[154:157], v[210:213], v[110:113]
	v_mfma_f32_16x16x32_bf16 v[106:109], v[158:161], v[190:193], v[106:109]
	v_mfma_f32_16x16x32_bf16 v[106:109], v[162:165], v[210:213], v[106:109]
	v_mfma_f32_16x16x32_bf16 v[94:97], v[142:145], v[228:231], v[94:97]
	v_mfma_f32_16x16x32_bf16 v[94:97], v[154:157], v[232:235], v[94:97]
	v_mfma_f32_16x16x32_bf16 v[90:93], v[158:161], v[228:231], v[90:93]
	v_mfma_f32_16x16x32_bf16 v[90:93], v[162:165], v[232:235], v[90:93]
	v_mfma_f32_16x16x32_bf16 v[78:81], v[142:145], v[236:239], v[78:81]
	v_mfma_f32_16x16x32_bf16 v[78:81], v[154:157], v[240:243], v[78:81]
	v_mfma_f32_16x16x32_bf16 v[74:77], v[158:161], v[236:239], v[74:77]
	v_mfma_f32_16x16x32_bf16 v[74:77], v[162:165], v[240:243], v[74:77]
	s_setprio 0
	s_cmp_eq_u32 s53, 18
	s_cbranch_scc1 .Linp_skip_2
	s_setprio 1
	v_mfma_f32_16x16x32_bf16 v[118:121], v[166:169], v[182:185], v[118:121]
	v_mfma_f32_16x16x32_bf16 v[118:121], v[170:173], v[186:189], v[118:121]
	v_mfma_f32_16x16x32_bf16 v[114:117], v[174:177], v[182:185], v[114:117]
	v_mfma_f32_16x16x32_bf16 v[114:117], v[178:181], v[186:189], v[114:117]
	v_mfma_f32_16x16x32_bf16 v[102:105], v[166:169], v[190:193], v[102:105]
	v_mfma_f32_16x16x32_bf16 v[102:105], v[170:173], v[210:213], v[102:105]
	v_mfma_f32_16x16x32_bf16 v[98:101], v[174:177], v[190:193], v[98:101]
	v_mfma_f32_16x16x32_bf16 v[98:101], v[178:181], v[210:213], v[98:101]
	v_mfma_f32_16x16x32_bf16 v[86:89], v[166:169], v[228:231], v[86:89]
	v_mfma_f32_16x16x32_bf16 v[86:89], v[170:173], v[232:235], v[86:89]
	v_mfma_f32_16x16x32_bf16 v[82:85], v[174:177], v[228:231], v[82:85]
	v_mfma_f32_16x16x32_bf16 v[82:85], v[178:181], v[232:235], v[82:85]
	v_mfma_f32_16x16x32_bf16 v[70:73], v[166:169], v[236:239], v[70:73]
	v_mfma_f32_16x16x32_bf16 v[70:73], v[170:173], v[240:243], v[70:73]
	v_mfma_f32_16x16x32_bf16 v[66:69], v[174:177], v[236:239], v[66:69]
	v_mfma_f32_16x16x32_bf16 v[66:69], v[178:181], v[240:243], v[66:69]
	s_setprio 0
; #define PG8_STAGE(bufoff, gbase, voff) do { _Pragma("unroll") for (int _i = 0; _i < 2; ++_i) \
;         __builtin_amdgcn_global_load_lds((const unsigned*)((const char*)(gbase) + (voff)[_i]), (PG8_LAS unsigned*)(lds + (bufoff) + ldsw + _i * 8192), 16, 0, 0); } while (0)
; #define PG8_LDA(dst, b, h) do { _Pragma("unroll") for (int m = 0; m < 4; ++m) _Pragma("unroll") for (int k = 0; k < 2; ++k) dst[m][k] = *(const PG8_LAS bf16x8*)(lds + PG8_SA(b, h) + aoff + m * 2048 + k * 1024); } while (0)
; #define PG8_MMA(ai, bj, At, Bt) do { __builtin_amdgcn_s_setprio(1); _Pragma("unroll") for (int m = 0; m < 4; ++m) _Pragma("unroll") for (int n = 0; n < 2; ++n) _Pragma("unroll") for (int k = 0; k < 2; ++k) \
;         acc[ai][bj][m][n] = __builtin_amdgcn_mfma_f32_16x16x32_bf16(Bt[n][k], At[m][k], acc[ai][bj][m][n], 0, 0, 0); __builtin_amdgcn_s_setprio(0); } while (0)
; #define PG8_WAIT_V(n) asm volatile("s_waitcnt vmcnt(" #n ")" ::: "memory")
; #define PG8_WAIT_L(n) asm volatile("s_waitcnt lgkmcnt(" #n ")" ::: "memory")
; #define PG8_BAR __builtin_amdgcn_s_barrier()
; #define PG8_SCHED __builtin_amdgcn_sched_barrier(0)
; template <class Epi, class Sched, bool ALIGN_EPI = false, bool SP2 = false>
; __device__ __forceinline__ void gemm_phase(PG8_LAS unsigned char* lds, const Gemm g, const Sched& S, const Epi& E) {
;     ...
;             PG8_LDA(At, 1, 1); PG8_STAGE(PG8_SB(1, 0), b3, voffB); PG8_STAGE(PG8_SB(1, 1), b3 + hstepB, voffB); PG8_STAGE(PG8_SA(1, 0), a3, voffA);
;             PG8_WAIT_V(8); PG8_WAIT_L(0); PG8_BAR; PG8_MMA(1, 0, At, B0); PG8_MMA(1, 1, At, B1); PG8_BAR; PG8_SCHED;
.Linp_skip_2:
	s_barrier
	s_add_i32 s2, s2, s36
	v_lshl_add_u64 v[146:147], v[146:147], 0, s[94:95]
	s_mov_b32 m0, s2
	ds_read_b128 v[182:185], v152 offset:49152
	ds_read_b128 v[186:189], v152 offset:50176
	ds_read_b128 v[190:193], v152 offset:51200
	ds_read_b128 v[210:213], v152 offset:52224
	ds_read_b128 v[228:231], v152 offset:53248
	ds_read_b128 v[232:235], v152 offset:54272
	ds_read_b128 v[236:239], v152 offset:55296
	ds_read_b128 v[240:243], v152 offset:56320
	global_load_lds_dwordx4 v[146:147], off
	s_add_i32 m0, s2, 0x2000
	s_add_u32 s42, s42, 0x80080
	v_lshl_add_u64 v[146:147], v[194:195], 0, s[94:95]
	s_addc_u32 s43, s43, 0
	s_add_i32 s2, s33, s36
	global_load_lds_dwordx4 v[146:147], off
	v_lshl_add_u64 v[146:147], s[42:43], 0, v[0:1]
	s_mov_b32 m0, s2
	s_nop 0
	global_load_lds_dwordx4 v[146:147], off
	v_lshl_add_u64 v[146:147], s[42:43], 0, v[132:133]
	s_add_i32 m0, s2, 0x2000
	s_nop 0
	global_load_lds_dwordx4 v[146:147], off
	v_lshl_add_u64 v[146:147], v[214:215], 0, s[94:95]
	s_mov_b32 m0, s50
	s_nop 0
	global_load_lds_dwordx4 v[146:147], off
	v_lshl_add_u64 v[146:147], v[222:223], 0, s[94:95]
	s_mov_b32 m0, s51
	s_nop 0
	global_load_lds_dwordx4 v[146:147], off
	s_waitcnt vmcnt(8)
	s_waitcnt lgkmcnt(0)
	s_barrier
	s_setprio 1
	s_waitcnt lgkmcnt(0)
	v_mfma_f32_16x16x32_bf16 v[62:65], v[142:145], v[182:185], v[62:65]
	v_mfma_f32_16x16x32_bf16 v[62:65], v[154:157], v[186:189], v[62:65]
	v_mfma_f32_16x16x32_bf16 v[58:61], v[158:161], v[182:185], v[58:61]
	v_mfma_f32_16x16x32_bf16 v[58:61], v[162:165], v[186:189], v[58:61]
	v_mfma_f32_16x16x32_bf16 v[46:49], v[142:145], v[190:193], v[46:49]
	v_mfma_f32_16x16x32_bf16 v[46:49], v[154:157], v[210:213], v[46:49]
	v_mfma_f32_16x16x32_bf16 v[42:45], v[158:161], v[190:193], v[42:45]
	v_mfma_f32_16x16x32_bf16 v[42:45], v[162:165], v[210:213], v[42:45]
	v_mfma_f32_16x16x32_bf16 v[30:33], v[142:145], v[228:231], v[30:33]
	v_mfma_f32_16x16x32_bf16 v[30:33], v[154:157], v[232:235], v[30:33]
	v_mfma_f32_16x16x32_bf16 v[26:29], v[158:161], v[228:231], v[26:29]
	v_mfma_f32_16x16x32_bf16 v[26:29], v[162:165], v[232:235], v[26:29]
	v_mfma_f32_16x16x32_bf16 v[14:17], v[142:145], v[236:239], v[14:17]
	v_mfma_f32_16x16x32_bf16 v[14:17], v[154:157], v[240:243], v[14:17]
	v_mfma_f32_16x16x32_bf16 v[10:13], v[158:161], v[236:239], v[10:13]
	v_mfma_f32_16x16x32_bf16 v[10:13], v[162:165], v[240:243], v[10:13]
	s_setprio 0
	s_cmp_eq_u32 s53, 18
	s_cbranch_scc1 .Linp_skip_3
	s_setprio 1
	v_mfma_f32_16x16x32_bf16 v[54:57], v[166:169], v[182:185], v[54:57]
	v_mfma_f32_16x16x32_bf16 v[54:57], v[170:173], v[186:189], v[54:57]
	v_mfma_f32_16x16x32_bf16 v[50:53], v[174:177], v[182:185], v[50:53]
	v_mfma_f32_16x16x32_bf16 v[50:53], v[178:181], v[186:189], v[50:53]
	v_mfma_f32_16x16x32_bf16 v[38:41], v[166:169], v[190:193], v[38:41]
	v_mfma_f32_16x16x32_bf16 v[38:41], v[170:173], v[210:213], v[38:41]
	v_mfma_f32_16x16x32_bf16 v[34:37], v[174:177], v[190:193], v[34:37]
	v_mfma_f32_16x16x32_bf16 v[34:37], v[178:181], v[210:213], v[34:37]
	v_mfma_f32_16x16x32_bf16 v[22:25], v[166:169], v[228:231], v[22:25]
	v_mfma_f32_16x16x32_bf16 v[22:25], v[170:173], v[232:235], v[22:25]
	v_mfma_f32_16x16x32_bf16 v[18:21], v[174:177], v[228:231], v[18:21]
	v_mfma_f32_16x16x32_bf16 v[18:21], v[178:181], v[232:235], v[18:21]
	v_mfma_f32_16x16x32_bf16 v[6:9], v[166:169], v[236:239], v[6:9]
	v_mfma_f32_16x16x32_bf16 v[6:9], v[170:173], v[240:243], v[6:9]
	v_mfma_f32_16x16x32_bf16 v[2:5], v[174:177], v[236:239], v[2:5]
	v_mfma_f32_16x16x32_bf16 v[2:5], v[178:181], v[240:243], v[2:5]
	s_setprio 0
